# v61 + one static s_setprio 1 for waves 4-7 in all four GEMM phases, per-segment priority flips removed
# baseline (speedup 1.0000x reference)
; __global__ void __launch_bounds__(NTHREADS, 2) fwd(Args a) {
;     ...
;     for (int ph = a.lo; ph < a.hi; ++ph) {
;         if (ph > a.lo) xcd_barrier(xbar);
.LBB0_8:
	s_setprio 0
	v_readlane_b32 s28, v255, 14
	s_add_i32 s57, s57, 1
	v_readlane_b32 s29, v255, 15
	s_cmp_ge_i32 s57, s29
	s_cbranch_scc0 .LBB0_9
	s_getpc_b64 s[98:99]

; #define PG8_WAIT_V(n) asm volatile("s_waitcnt vmcnt(" #n ")" ::: "memory")
; #define PG8_BAR __builtin_amdgcn_s_barrier()
; template <class Epi, bool ALIGN_EPI = true>
; __device__ __forceinline__ void gemm_phase(LAS unsigned char* lds, const Gemm g, const Order& S, const Epi& E) {
;     ...
;     if constexpr (Epi::PRELOAD) { E.preload(pre, S, tid); __syncthreads(); }
;     if (wr == 1) PG8_BAR;
;     PG8_WAIT_V(2); PG8_BAR;
.LBB0_179:
	s_or_b64 exec, exec, s[36:37]
	s_ashr_i32 s36, s34, 8
	s_cmp_eq_u32 s36, 1
	s_cselect_b64 s[46:47], -1, 0
	s_cmp_lg_u32 s36, 1
	s_waitcnt vmcnt(0)
	ds_write2st64_b32 v103, v101, v104 offset0:32 offset1:40
	s_waitcnt lgkmcnt(0)
	s_barrier
	s_cbranch_scc1 .LBB0_181
	s_setprio 1
	s_barrier

; #define PG8_STAGE(bufoff, gbase, voff) do { _Pragma("unroll") for (int _i = 0; _i < 2; ++_i) \
;         __builtin_amdgcn_global_load_lds((const unsigned*)((const char*)(gbase) + (voff)[_i]), (LAS unsigned*)(lds + (bufoff) + ldsw + _i * 8192), 16, 0, 0); } while (0)
; #define PG8_LDA(dst, b, h) do { _Pragma("unroll") for (int m = 0; m < 4; ++m) _Pragma("unroll") for (int k = 0; k < 2; ++k) dst[m][k] = *(const LAS bf16x8*)(lds + PG8_SA(b, h) + aoff + m * 2048 + k * 1024); } while (0)
; #define PG8_LDB(dst, b, h) do { _Pragma("unroll") for (int n = 0; n < 2; ++n) _Pragma("unroll") for (int k = 0; k < 2; ++k) dst[n][k] = *(const LAS bf16x8*)(lds + PG8_SB(b, h) + boff + n * 2048 + k * 1024); } while (0)
; #define PG8_MMA(ai, bj, At, Bt) do { __builtin_amdgcn_s_setprio(1); _Pragma("unroll") for (int m = 0; m < 4; ++m) _Pragma("unroll") for (int n = 0; n < 2; ++n) _Pragma("unroll") for (int k = 0; k < 2; ++k) \
;         acc[ai][bj][m][n] = __builtin_amdgcn_mfma_f32_16x16x32_bf16(Bt[n][k], At[m][k], acc[ai][bj][m][n], 0, 0, 0); __builtin_amdgcn_s_setprio(0); } while (0)
; #define PG8_WAIT_V(n) asm volatile("s_waitcnt vmcnt(" #n ")" ::: "memory")
; #define PG8_WAIT_L(n) asm volatile("s_waitcnt lgkmcnt(" #n ")" ::: "memory")
; #define PG8_BAR __builtin_amdgcn_s_barrier()
; #define PG8_SCHED __builtin_amdgcn_sched_barrier(0)
; template <class Epi, bool ALIGN_EPI = true>
; __device__ __forceinline__ void gemm_phase(LAS unsigned char* lds, const Gemm g, const Order& S, const Epi& E) {
;     ...
;             const char* a1 = cA + (size_t)(t + 1) * kstepA;
;             const char* a2 = last ? nA : cA + (size_t)(t + 2) * kstepA; const char* b2 = last ? nB : cB + (size_t)(t + 2) * kstepB;
;             const char* a3 = a2 + kstepA; const char* b3 = b2 + kstepB;
;             PG8_LDB(B0, 0, 0); PG8_LDB(B1, 0, 1); PG8_SCHED; PG8_LDA(At, 0, 0); PG8_STAGE(PG8_SA(1, 1), a1 + hstepA, voffA);
;             PG8_WAIT_V(8); PG8_WAIT_L(0); PG8_BAR; PG8_MMA(0, 0, At, B0); PG8_MMA(0, 1, At, B1); PG8_BAR; PG8_SCHED;
;             PG8_LDA(At, 0, 1); PG8_STAGE(PG8_SB(0, 0), b2, voffB); PG8_STAGE(PG8_SB(0, 1), b2 + hstepB, voffB); PG8_STAGE(PG8_SA(0, 0), a2, voffA);
;             PG8_WAIT_V(8); PG8_WAIT_L(0); PG8_BAR; PG8_MMA(1, 0, At, B0); PG8_MMA(1, 1, At, B1); PG8_BAR; PG8_SCHED;
.LBB0_186:
	s_add_u32 s60, s44, s58
	s_addc_u32 s61, s45, s59
	s_add_u32 s60, s60, 0x10000
	s_addc_u32 s61, s61, 0
	s_add_u32 s62, s90, s58
	s_addc_u32 s63, s91, s59
	s_cmp_eq_u32 s58, 0x70000
	s_cselect_b32 s64, s35, s60
	s_cselect_b32 s65, s34, s61
	s_cselect_b32 s62, s53, s62
	s_cselect_b32 s63, s51, s63
	s_add_u32 s60, s64, 0x8000
	s_addc_u32 s61, s65, 0
	s_add_i32 s93, 0, 0x10000
	s_add_i32 s96, 0, 0x14000
	v_add_u32_e32 v146, s93, v169
	v_add_u32_e32 v164, s96, v169
	ds_read_b128 v[134:137], v146
	ds_read_b128 v[138:141], v146 offset:1024
	ds_read_b128 v[142:145], v146 offset:2048
	ds_read_b128 v[146:149], v146 offset:3072
	ds_read_b128 v[150:153], v164
	ds_read_b128 v[154:157], v164 offset:1024
	ds_read_b128 v[178:181], v164 offset:2048
	ds_read_b128 v[182:185], v164 offset:3072
	v_lshl_add_u64 v[220:221], v[130:131], 0, s[58:59]
	s_add_i32 m0, s5, 0xc000
	ds_read_b128 v[186:189], v177
	ds_read_b128 v[190:193], v177 offset:1024
	ds_read_b128 v[194:197], v177 offset:2048
	ds_read_b128 v[198:201], v177 offset:3072
	ds_read_b128 v[202:205], v177 offset:4096
	ds_read_b128 v[208:211], v177 offset:5120
	ds_read_b128 v[212:215], v177 offset:6144
	ds_read_b128 v[216:219], v177 offset:7168
	global_load_lds_dwordx4 v[220:221], off
	v_lshl_add_u64 v[220:221], v[132:133], 0, s[58:59]
	s_add_i32 m0, s5, 0xe000
	s_nop 0
	global_load_lds_dwordx4 v[220:221], off
	s_waitcnt vmcnt(8)
	s_waitcnt lgkmcnt(0)
	s_barrier
	s_waitcnt lgkmcnt(0)
	v_mfma_f32_16x16x32_bf16 v[126:129], v[134:137], v[186:189], v[126:129]
	v_mfma_f32_16x16x32_bf16 v[122:125], v[142:145], v[186:189], v[122:125]
	v_mfma_f32_16x16x32_bf16 v[118:121], v[134:137], v[194:197], v[118:121]
	v_mfma_f32_16x16x32_bf16 v[114:117], v[142:145], v[194:197], v[114:117]
	v_mfma_f32_16x16x32_bf16 v[110:113], v[134:137], v[202:205], v[110:113]
	v_mfma_f32_16x16x32_bf16 v[106:109], v[142:145], v[202:205], v[106:109]
	v_mfma_f32_16x16x32_bf16 v[102:105], v[134:137], v[212:215], v[102:105]
	v_mfma_f32_16x16x32_bf16 v[98:101], v[142:145], v[212:215], v[98:101]
	v_mfma_f32_16x16x32_bf16 v[126:129], v[138:141], v[190:193], v[126:129]
	v_mfma_f32_16x16x32_bf16 v[122:125], v[146:149], v[190:193], v[122:125]
	v_mfma_f32_16x16x32_bf16 v[118:121], v[138:141], v[198:201], v[118:121]
	v_mfma_f32_16x16x32_bf16 v[114:117], v[146:149], v[198:201], v[114:117]
	v_mfma_f32_16x16x32_bf16 v[110:113], v[138:141], v[208:211], v[110:113]
	v_mfma_f32_16x16x32_bf16 v[106:109], v[146:149], v[208:211], v[106:109]
	v_mfma_f32_16x16x32_bf16 v[102:105], v[138:141], v[216:219], v[102:105]
	v_mfma_f32_16x16x32_bf16 v[98:101], v[146:149], v[216:219], v[98:101]
	v_mfma_f32_16x16x32_bf16 v[94:97], v[150:153], v[186:189], v[94:97]
	v_mfma_f32_16x16x32_bf16 v[90:93], v[178:181], v[186:189], v[90:93]
	v_mfma_f32_16x16x32_bf16 v[86:89], v[150:153], v[194:197], v[86:89]
	v_mfma_f32_16x16x32_bf16 v[82:85], v[178:181], v[194:197], v[82:85]
	v_mfma_f32_16x16x32_bf16 v[78:81], v[150:153], v[202:205], v[78:81]
	v_mfma_f32_16x16x32_bf16 v[74:77], v[178:181], v[202:205], v[74:77]
	v_mfma_f32_16x16x32_bf16 v[70:73], v[150:153], v[212:215], v[70:73]
	v_mfma_f32_16x16x32_bf16 v[66:69], v[178:181], v[212:215], v[66:69]
	v_mfma_f32_16x16x32_bf16 v[94:97], v[154:157], v[190:193], v[94:97]
	v_mfma_f32_16x16x32_bf16 v[90:93], v[182:185], v[190:193], v[90:93]
	v_mfma_f32_16x16x32_bf16 v[86:89], v[154:157], v[198:201], v[86:89]
	v_mfma_f32_16x16x32_bf16 v[82:85], v[182:185], v[198:201], v[82:85]
	v_mfma_f32_16x16x32_bf16 v[78:81], v[154:157], v[208:211], v[78:81]
	v_mfma_f32_16x16x32_bf16 v[74:77], v[182:185], v[208:211], v[74:77]
	v_mfma_f32_16x16x32_bf16 v[70:73], v[154:157], v[216:219], v[70:73]
	v_mfma_f32_16x16x32_bf16 v[66:69], v[182:185], v[216:219], v[66:69]
	s_barrier
	s_add_i32 s93, s93, s72
	v_lshl_add_u64 v[220:221], s[62:63], 0, v[158:159]
	s_mov_b32 m0, s93
	ds_read_b128 v[186:189], v177 offset:16384
	ds_read_b128 v[190:193], v177 offset:17408
	ds_read_b128 v[194:197], v177 offset:18432
	ds_read_b128 v[198:201], v177 offset:19456
	ds_read_b128 v[202:205], v177 offset:20480
	ds_read_b128 v[208:211], v177 offset:21504
	ds_read_b128 v[212:215], v177 offset:22528
	ds_read_b128 v[216:219], v177 offset:23552
	global_load_lds_dwordx4 v[220:221], off
	s_add_i32 m0, s93, 0x2000
	s_add_u32 s94, s62, 0x4000
	v_lshl_add_u64 v[220:221], s[62:63], 0, v[160:161]
	s_addc_u32 s95, s63, 0
	s_add_i32 s93, s96, s72
	global_load_lds_dwordx4 v[220:221], off
	v_lshl_add_u64 v[220:221], s[94:95], 0, v[158:159]
	s_mov_b32 m0, s93
	s_nop 0
	global_load_lds_dwordx4 v[220:221], off
	v_lshl_add_u64 v[220:221], s[94:95], 0, v[160:161]
	s_add_i32 m0, s93, 0x2000
	s_nop 0
	global_load_lds_dwordx4 v[220:221], off
	v_lshl_add_u64 v[220:221], s[64:65], 0, v[158:159]
	s_mov_b32 m0, s5
	s_nop 0
	global_load_lds_dwordx4 v[220:221], off
	v_lshl_add_u64 v[220:221], s[64:65], 0, v[160:161]
	s_mov_b32 m0, s41
	s_nop 0
	global_load_lds_dwordx4 v[220:221], off
	s_waitcnt vmcnt(8)
	s_waitcnt lgkmcnt(0)
	s_barrier
; #define PG8_STAGE(bufoff, gbase, voff) do { _Pragma("unroll") for (int _i = 0; _i < 2; ++_i) \
;         __builtin_amdgcn_global_load_lds((const unsigned*)((const char*)(gbase) + (voff)[_i]), (LAS unsigned*)(lds + (bufoff) + ldsw + _i * 8192), 16, 0, 0); } while (0)
; #define PG8_LDA(dst, b, h) do { _Pragma("unroll") for (int m = 0; m < 4; ++m) _Pragma("unroll") for (int k = 0; k < 2; ++k) dst[m][k] = *(const LAS bf16x8*)(lds + PG8_SA(b, h) + aoff + m * 2048 + k * 1024); } while (0)
; #define PG8_LDB(dst, b, h) do { _Pragma("unroll") for (int n = 0; n < 2; ++n) _Pragma("unroll") for (int k = 0; k < 2; ++k) dst[n][k] = *(const LAS bf16x8*)(lds + PG8_SB(b, h) + boff + n * 2048 + k * 1024); } while (0)
; #define PG8_MMA(ai, bj, At, Bt) do { __builtin_amdgcn_s_setprio(1); _Pragma("unroll") for (int m = 0; m < 4; ++m) _Pragma("unroll") for (int n = 0; n < 2; ++n) _Pragma("unroll") for (int k = 0; k < 2; ++k) \
;         acc[ai][bj][m][n] = __builtin_amdgcn_mfma_f32_16x16x32_bf16(Bt[n][k], At[m][k], acc[ai][bj][m][n], 0, 0, 0); __builtin_amdgcn_s_setprio(0); } while (0)
; #define PG8_WAIT_V(n) asm volatile("s_waitcnt vmcnt(" #n ")" ::: "memory")
; #define PG8_WAIT_L(n) asm volatile("s_waitcnt lgkmcnt(" #n ")" ::: "memory")
; #define PG8_BAR __builtin_amdgcn_s_barrier()
; #define PG8_SCHED __builtin_amdgcn_sched_barrier(0)
; template <class Epi, bool ALIGN_EPI = true>
; __device__ __forceinline__ void gemm_phase(LAS unsigned char* lds, const Gemm g, const Order& S, const Epi& E) {
;     ...
;             PG8_WAIT_V(8); PG8_WAIT_L(0); PG8_BAR; PG8_MMA(1, 0, At, B0); PG8_MMA(1, 1, At, B1); PG8_BAR; PG8_SCHED;
;             PG8_LDB(B0, 1, 0); PG8_LDB(B1, 1, 1); PG8_SCHED; PG8_LDA(At, 1, 0); PG8_STAGE(PG8_SA(0, 1), a2 + hstepA, voffA);
;             PG8_WAIT_V(8); PG8_WAIT_L(0); PG8_BAR; PG8_MMA(0, 0, At, B0); PG8_MMA(0, 1, At, B1); PG8_BAR; PG8_SCHED;
	s_waitcnt lgkmcnt(0)
	v_mfma_f32_16x16x32_bf16 v[62:65], v[134:137], v[186:189], v[62:65]
	v_mfma_f32_16x16x32_bf16 v[58:61], v[142:145], v[186:189], v[58:61]
	v_mfma_f32_16x16x32_bf16 v[54:57], v[134:137], v[194:197], v[54:57]
	v_mfma_f32_16x16x32_bf16 v[50:53], v[142:145], v[194:197], v[50:53]
	v_mfma_f32_16x16x32_bf16 v[46:49], v[134:137], v[202:205], v[46:49]
	v_mfma_f32_16x16x32_bf16 v[42:45], v[142:145], v[202:205], v[42:45]
	v_mfma_f32_16x16x32_bf16 v[38:41], v[134:137], v[212:215], v[38:41]
	v_mfma_f32_16x16x32_bf16 v[34:37], v[142:145], v[212:215], v[34:37]
	v_mfma_f32_16x16x32_bf16 v[62:65], v[138:141], v[190:193], v[62:65]
	v_mfma_f32_16x16x32_bf16 v[58:61], v[146:149], v[190:193], v[58:61]
	v_mfma_f32_16x16x32_bf16 v[54:57], v[138:141], v[198:201], v[54:57]
	v_mfma_f32_16x16x32_bf16 v[50:53], v[146:149], v[198:201], v[50:53]
	v_mfma_f32_16x16x32_bf16 v[46:49], v[138:141], v[208:211], v[46:49]
	v_mfma_f32_16x16x32_bf16 v[42:45], v[146:149], v[208:211], v[42:45]
	v_mfma_f32_16x16x32_bf16 v[38:41], v[138:141], v[216:219], v[38:41]
	v_mfma_f32_16x16x32_bf16 v[34:37], v[146:149], v[216:219], v[34:37]
	v_mfma_f32_16x16x32_bf16 v[30:33], v[150:153], v[186:189], v[30:33]
	v_mfma_f32_16x16x32_bf16 v[26:29], v[178:181], v[186:189], v[26:29]
	v_mfma_f32_16x16x32_bf16 v[22:25], v[150:153], v[194:197], v[22:25]
	v_mfma_f32_16x16x32_bf16 v[18:21], v[178:181], v[194:197], v[18:21]
	v_mfma_f32_16x16x32_bf16 v[14:17], v[150:153], v[202:205], v[14:17]
	v_mfma_f32_16x16x32_bf16 v[10:13], v[178:181], v[202:205], v[10:13]
	v_mfma_f32_16x16x32_bf16 v[6:9], v[150:153], v[212:215], v[6:9]
	v_mfma_f32_16x16x32_bf16 v[2:5], v[178:181], v[212:215], v[2:5]
	v_mfma_f32_16x16x32_bf16 v[30:33], v[154:157], v[190:193], v[30:33]
	v_mfma_f32_16x16x32_bf16 v[26:29], v[182:185], v[190:193], v[26:29]
	v_mfma_f32_16x16x32_bf16 v[22:25], v[154:157], v[198:201], v[22:25]
	v_mfma_f32_16x16x32_bf16 v[18:21], v[182:185], v[198:201], v[18:21]
	v_mfma_f32_16x16x32_bf16 v[14:17], v[154:157], v[208:211], v[14:17]
	v_mfma_f32_16x16x32_bf16 v[10:13], v[182:185], v[208:211], v[10:13]
	v_mfma_f32_16x16x32_bf16 v[6:9], v[154:157], v[216:219], v[6:9]
	v_mfma_f32_16x16x32_bf16 v[2:5], v[182:185], v[216:219], v[2:5]
	s_barrier
	s_add_i32 s93, 0, 0x18000
	s_add_i32 s94, 0, 0x1c000
	v_add_u32_e32 v146, s93, v169
	v_add_u32_e32 v164, s94, v169
	ds_read_b128 v[134:137], v146
	ds_read_b128 v[138:141], v146 offset:1024
	ds_read_b128 v[142:145], v146 offset:2048
	ds_read_b128 v[146:149], v146 offset:3072
	ds_read_b128 v[150:153], v164
	ds_read_b128 v[154:157], v164 offset:1024
	ds_read_b128 v[178:181], v164 offset:2048
	ds_read_b128 v[182:185], v164 offset:3072
	s_add_u32 s64, s64, 0x4000
	s_addc_u32 s65, s65, 0
	s_mov_b32 m0, s73
	v_lshl_add_u64 v[220:221], s[64:65], 0, v[158:159]
	ds_read_b128 v[186:189], v177 offset:32768
	ds_read_b128 v[190:193], v177 offset:33792
	ds_read_b128 v[194:197], v177 offset:34816
	ds_read_b128 v[198:201], v177 offset:35840
	ds_read_b128 v[202:205], v177 offset:36864
	ds_read_b128 v[208:211], v177 offset:37888
	ds_read_b128 v[212:215], v177 offset:38912
	ds_read_b128 v[216:219], v177 offset:39936
	global_load_lds_dwordx4 v[220:221], off
	v_lshl_add_u64 v[220:221], s[64:65], 0, v[160:161]
	s_mov_b32 m0, s74
	s_nop 0
	global_load_lds_dwordx4 v[220:221], off
	s_waitcnt vmcnt(8)
	s_waitcnt lgkmcnt(0)
	s_barrier
	s_waitcnt lgkmcnt(0)
	v_mfma_f32_16x16x32_bf16 v[126:129], v[134:137], v[186:189], v[126:129]
	v_mfma_f32_16x16x32_bf16 v[122:125], v[142:145], v[186:189], v[122:125]
	v_mfma_f32_16x16x32_bf16 v[118:121], v[134:137], v[194:197], v[118:121]
	v_mfma_f32_16x16x32_bf16 v[114:117], v[142:145], v[194:197], v[114:117]
	v_mfma_f32_16x16x32_bf16 v[110:113], v[134:137], v[202:205], v[110:113]
	v_mfma_f32_16x16x32_bf16 v[106:109], v[142:145], v[202:205], v[106:109]
	v_mfma_f32_16x16x32_bf16 v[102:105], v[134:137], v[212:215], v[102:105]
	v_mfma_f32_16x16x32_bf16 v[98:101], v[142:145], v[212:215], v[98:101]
	v_mfma_f32_16x16x32_bf16 v[126:129], v[138:141], v[190:193], v[126:129]
	v_mfma_f32_16x16x32_bf16 v[122:125], v[146:149], v[190:193], v[122:125]
	v_mfma_f32_16x16x32_bf16 v[118:121], v[138:141], v[198:201], v[118:121]
	v_mfma_f32_16x16x32_bf16 v[114:117], v[146:149], v[198:201], v[114:117]
	v_mfma_f32_16x16x32_bf16 v[110:113], v[138:141], v[208:211], v[110:113]
	v_mfma_f32_16x16x32_bf16 v[106:109], v[146:149], v[208:211], v[106:109]
	v_mfma_f32_16x16x32_bf16 v[102:105], v[138:141], v[216:219], v[102:105]
	v_mfma_f32_16x16x32_bf16 v[98:101], v[146:149], v[216:219], v[98:101]
	v_mfma_f32_16x16x32_bf16 v[94:97], v[150:153], v[186:189], v[94:97]
	v_mfma_f32_16x16x32_bf16 v[90:93], v[178:181], v[186:189], v[90:93]
	v_mfma_f32_16x16x32_bf16 v[86:89], v[150:153], v[194:197], v[86:89]
	v_mfma_f32_16x16x32_bf16 v[82:85], v[178:181], v[194:197], v[82:85]
	v_mfma_f32_16x16x32_bf16 v[78:81], v[150:153], v[202:205], v[78:81]
	v_mfma_f32_16x16x32_bf16 v[74:77], v[178:181], v[202:205], v[74:77]
	v_mfma_f32_16x16x32_bf16 v[70:73], v[150:153], v[212:215], v[70:73]
	v_mfma_f32_16x16x32_bf16 v[66:69], v[178:181], v[212:215], v[66:69]
	v_mfma_f32_16x16x32_bf16 v[94:97], v[154:157], v[190:193], v[94:97]
	v_mfma_f32_16x16x32_bf16 v[90:93], v[182:185], v[190:193], v[90:93]
	v_mfma_f32_16x16x32_bf16 v[86:89], v[154:157], v[198:201], v[86:89]
	v_mfma_f32_16x16x32_bf16 v[82:85], v[182:185], v[198:201], v[82:85]
	v_mfma_f32_16x16x32_bf16 v[78:81], v[154:157], v[208:211], v[78:81]
	v_mfma_f32_16x16x32_bf16 v[74:77], v[182:185], v[208:211], v[74:77]
	v_mfma_f32_16x16x32_bf16 v[70:73], v[154:157], v[216:219], v[70:73]
	v_mfma_f32_16x16x32_bf16 v[66:69], v[182:185], v[216:219], v[66:69]
	s_barrier
; #define PG8_STAGE(bufoff, gbase, voff) do { _Pragma("unroll") for (int _i = 0; _i < 2; ++_i) \
;         __builtin_amdgcn_global_load_lds((const unsigned*)((const char*)(gbase) + (voff)[_i]), (LAS unsigned*)(lds + (bufoff) + ldsw + _i * 8192), 16, 0, 0); } while (0)
; #define PG8_LDA(dst, b, h) do { _Pragma("unroll") for (int m = 0; m < 4; ++m) _Pragma("unroll") for (int k = 0; k < 2; ++k) dst[m][k] = *(const LAS bf16x8*)(lds + PG8_SA(b, h) + aoff + m * 2048 + k * 1024); } while (0)
; #define PG8_MMA(ai, bj, At, Bt) do { __builtin_amdgcn_s_setprio(1); _Pragma("unroll") for (int m = 0; m < 4; ++m) _Pragma("unroll") for (int n = 0; n < 2; ++n) _Pragma("unroll") for (int k = 0; k < 2; ++k) \
;         acc[ai][bj][m][n] = __builtin_amdgcn_mfma_f32_16x16x32_bf16(Bt[n][k], At[m][k], acc[ai][bj][m][n], 0, 0, 0); __builtin_amdgcn_s_setprio(0); } while (0)
; #define PG8_WAIT_V(n) asm volatile("s_waitcnt vmcnt(" #n ")" ::: "memory")
; #define PG8_WAIT_L(n) asm volatile("s_waitcnt lgkmcnt(" #n ")" ::: "memory")
; #define PG8_BAR __builtin_amdgcn_s_barrier()
; #define PG8_SCHED __builtin_amdgcn_sched_barrier(0)
; template <class Epi, bool ALIGN_EPI = true>
; __device__ __forceinline__ void gemm_phase(LAS unsigned char* lds, const Gemm g, const Order& S, const Epi& E) {
;     ...
;             PG8_LDA(At, 1, 1); PG8_STAGE(PG8_SB(1, 0), b3, voffB); PG8_STAGE(PG8_SB(1, 1), b3 + hstepB, voffB); PG8_STAGE(PG8_SA(1, 0), a3, voffA);
;             PG8_WAIT_V(8); PG8_WAIT_L(0); PG8_BAR; PG8_MMA(1, 0, At, B0); PG8_MMA(1, 1, At, B1); PG8_BAR; PG8_SCHED;
;         }
;         if constexpr (ALIGN_EPI) { if (wr == 0) PG8_BAR; }
	s_add_u32 s64, s62, 0x8000
	s_addc_u32 s65, s63, 0
	s_add_i32 s93, s93, s72
	v_lshl_add_u64 v[220:221], s[64:65], 0, v[158:159]
	s_mov_b32 m0, s93
	ds_read_b128 v[186:189], v177 offset:49152
	ds_read_b128 v[190:193], v177 offset:50176
	ds_read_b128 v[194:197], v177 offset:51200
	ds_read_b128 v[198:201], v177 offset:52224
	ds_read_b128 v[202:205], v177 offset:53248
	ds_read_b128 v[208:211], v177 offset:54272
	ds_read_b128 v[212:215], v177 offset:55296
	ds_read_b128 v[216:219], v177 offset:56320
	global_load_lds_dwordx4 v[220:221], off
	s_add_i32 m0, s93, 0x2000
	s_add_u32 s62, s62, 0xc000
	v_lshl_add_u64 v[220:221], s[64:65], 0, v[160:161]
	s_addc_u32 s63, s63, 0
	s_add_i32 s64, s94, s72
	global_load_lds_dwordx4 v[220:221], off
	v_lshl_add_u64 v[220:221], s[62:63], 0, v[158:159]
	s_mov_b32 m0, s64
	s_nop 0
	global_load_lds_dwordx4 v[220:221], off
	v_lshl_add_u64 v[220:221], s[62:63], 0, v[160:161]
	s_add_i32 m0, s64, 0x2000
	s_nop 0
	global_load_lds_dwordx4 v[220:221], off
	v_lshl_add_u64 v[220:221], s[60:61], 0, v[158:159]
	s_mov_b32 m0, s79
	s_nop 0
	global_load_lds_dwordx4 v[220:221], off
	v_lshl_add_u64 v[220:221], s[60:61], 0, v[160:161]
	s_mov_b32 m0, s80
	s_nop 0
	global_load_lds_dwordx4 v[220:221], off
	s_waitcnt vmcnt(8)
	s_waitcnt lgkmcnt(0)
	s_barrier
	s_waitcnt lgkmcnt(0)
	v_mfma_f32_16x16x32_bf16 v[62:65], v[134:137], v[186:189], v[62:65]
	v_mfma_f32_16x16x32_bf16 v[58:61], v[142:145], v[186:189], v[58:61]
	v_mfma_f32_16x16x32_bf16 v[54:57], v[134:137], v[194:197], v[54:57]
	v_mfma_f32_16x16x32_bf16 v[50:53], v[142:145], v[194:197], v[50:53]
	v_mfma_f32_16x16x32_bf16 v[46:49], v[134:137], v[202:205], v[46:49]
	v_mfma_f32_16x16x32_bf16 v[42:45], v[142:145], v[202:205], v[42:45]
	v_mfma_f32_16x16x32_bf16 v[38:41], v[134:137], v[212:215], v[38:41]
	v_mfma_f32_16x16x32_bf16 v[34:37], v[142:145], v[212:215], v[34:37]
	v_mfma_f32_16x16x32_bf16 v[62:65], v[138:141], v[190:193], v[62:65]
	v_mfma_f32_16x16x32_bf16 v[58:61], v[146:149], v[190:193], v[58:61]
	v_mfma_f32_16x16x32_bf16 v[54:57], v[138:141], v[198:201], v[54:57]
	v_mfma_f32_16x16x32_bf16 v[50:53], v[146:149], v[198:201], v[50:53]
	v_mfma_f32_16x16x32_bf16 v[46:49], v[138:141], v[208:211], v[46:49]
	v_mfma_f32_16x16x32_bf16 v[42:45], v[146:149], v[208:211], v[42:45]
	v_mfma_f32_16x16x32_bf16 v[38:41], v[138:141], v[216:219], v[38:41]
	v_mfma_f32_16x16x32_bf16 v[34:37], v[146:149], v[216:219], v[34:37]
	v_mfma_f32_16x16x32_bf16 v[30:33], v[150:153], v[186:189], v[30:33]
	v_mfma_f32_16x16x32_bf16 v[26:29], v[178:181], v[186:189], v[26:29]
	v_mfma_f32_16x16x32_bf16 v[22:25], v[150:153], v[194:197], v[22:25]
	v_mfma_f32_16x16x32_bf16 v[18:21], v[178:181], v[194:197], v[18:21]
	v_mfma_f32_16x16x32_bf16 v[14:17], v[150:153], v[202:205], v[14:17]
	v_mfma_f32_16x16x32_bf16 v[10:13], v[178:181], v[202:205], v[10:13]
	v_mfma_f32_16x16x32_bf16 v[6:9], v[150:153], v[212:215], v[6:9]
	v_mfma_f32_16x16x32_bf16 v[2:5], v[178:181], v[212:215], v[2:5]
	v_mfma_f32_16x16x32_bf16 v[30:33], v[154:157], v[190:193], v[30:33]
	v_mfma_f32_16x16x32_bf16 v[26:29], v[182:185], v[190:193], v[26:29]
	v_mfma_f32_16x16x32_bf16 v[22:25], v[154:157], v[198:201], v[22:25]
	v_mfma_f32_16x16x32_bf16 v[18:21], v[182:185], v[198:201], v[18:21]
	v_mfma_f32_16x16x32_bf16 v[14:17], v[154:157], v[208:211], v[14:17]
	v_mfma_f32_16x16x32_bf16 v[10:13], v[182:185], v[208:211], v[10:13]
	v_mfma_f32_16x16x32_bf16 v[6:9], v[154:157], v[216:219], v[6:9]
	v_mfma_f32_16x16x32_bf16 v[2:5], v[182:185], v[216:219], v[2:5]
	s_barrier
	s_add_i32 s92, s92, 2
	s_add_u32 s58, s58, 0x10000
	s_addc_u32 s59, s59, 0
	s_cmp_gt_u32 s92, 13
	s_cbranch_scc0 .LBB0_186
	s_and_b64 vcc, exec, s[48:49]
	s_cbranch_vccz .LBB0_189
	s_barrier

; #define PG8_STAGE(bufoff, gbase, voff) do { _Pragma("unroll") for (int _i = 0; _i < 2; ++_i) \
;         __builtin_amdgcn_global_load_lds((const unsigned*)((const char*)(gbase) + (voff)[_i]), (LAS unsigned*)(lds + (bufoff) + ldsw + _i * 8192), 16, 0, 0); } while (0)
; #define PG8_BAR __builtin_amdgcn_s_barrier()
; template <class Epi, bool ALIGN_EPI = true>
; __device__ __forceinline__ void gemm_phase(LAS unsigned char* lds, const Gemm g, const Order& S, const Epi& E) {
;     ...
;     const char* cA = (const char*)g.A + (size_t)cur.pm * tstepA + (size_t)(cur.k0 >> 6) * kstepA; const char* cB = (const char*)g.Bt + (size_t)cur.pn * tstepB + (size_t)(cur.k0 >> 6) * kstepB;
;     PG8_STAGE(PG8_SB(0, 0), cB, voffB); PG8_STAGE(PG8_SB(0, 1), cB + hstepB, voffB); PG8_STAGE(PG8_SA(0, 0), cA, voffA); PG8_STAGE(PG8_SA(0, 1), cA + hstepA, voffA);
;     if constexpr (Epi::PRELOAD) { E.preload(pre, S, tid); __syncthreads(); }
;     if (wr == 1) PG8_BAR;
; __global__ void __launch_bounds__(NTHREADS, 2) fwd(Args a) {
;     ...
;             const float* tab = (const float*)(a.ws + WS_TAB) + (size_t)(2 * l + 1) * 15 * DM;
;             pg8::Gemm g{(const bf16_t*)(a.ws + WS_H), (const bf16_t*)(wl + WT_2), DFF, 64, HP, slab, (size_t)256 * 64 * 2, (size_t)256 * DFF * 2};
;             pg8::Order S; S.init(64, 4, G, bx, lastl ? 0 : 16 * 8, 64, DFF / 64, 8);
;             pg8::EpiRes E{(bf16_t*)(a.ws + WS_XG), ss, tab};
;             pg8::gemm_phase<pg8::EpiRes>(lds, g, S, E);
.LBB0_226:
	v_readlane_b32 s8, v255, 18
	s_lshl_b32 s40, s8, 1
	s_or_b32 s40, s40, 1
	s_mov_b32 s56, s28
	s_mul_hi_i32 s41, s40, 0xf000
	s_mul_i32 s40, s40, 0xf000
	v_readlane_b32 s28, v252, 30
	v_readlane_b32 s29, v252, 31
	s_add_u32 s67, s28, s40
	s_addc_u32 s68, s29, s41
	s_andn2_b64 vcc, exec, s[38:39]
	v_readlane_b32 s9, v255, 19
	s_cbranch_vccnz .LBB0_271
	v_writelane_b32 v255, s57, 20
	s_add_u32 s69, s10, 0xd80000
	v_readlane_b32 s8, v255, 22
	s_addc_u32 s70, s8, 0
	s_ashr_i32 s39, s1, 6
	s_ashr_i32 s57, s56, 31
	s_ashr_i32 s38, s1, 8
	s_lshl_b32 s71, s39, 10
	s_lshl_b64 s[40:41], s[56:57], 21
	s_add_u32 s44, s58, s40
	s_addc_u32 s45, s59, s41
	s_ashr_i32 s55, s54, 31
	s_lshl_b64 s[40:41], s[54:55], 21
	s_add_u32 s40, s69, s40
	s_addc_u32 s41, s70, s41
	s_add_u32 s60, s40, s4
	s_addc_u32 s61, s41, s5
	s_add_i32 s72, s71, 0
	v_lshlrev_b32_e32 v210, 4, v2
	s_add_i32 m0, s72, 0x10000
	v_add_u32_e32 v212, 0x2000, v210
	global_load_lds_dwordx4 v210, s[60:61]
	s_add_i32 m0, s72, 0x12000
	s_add_u32 s40, s60, 0x4000
	global_load_lds_dwordx4 v212, s[60:61]
	s_addc_u32 s41, s61, 0
	s_add_i32 m0, s72, 0x14000
	v_readlane_b32 s64, v254, 9
	global_load_lds_dwordx4 v210, s[40:41]
	s_add_i32 m0, s72, 0x16000
	s_add_u32 s58, s44, s4
	s_addc_u32 s59, s45, s5
	s_add_i32 s73, s72, 0x2000
	global_load_lds_dwordx4 v212, s[40:41]
	s_mov_b32 m0, s72
	s_add_u32 s4, s58, 0x4000
	global_load_lds_dwordx4 v210, s[58:59]
	s_mov_b32 m0, s73
	s_addc_u32 s5, s59, 0
	s_add_i32 s74, s72, 0x4000
	global_load_lds_dwordx4 v212, s[58:59]
	s_mov_b32 m0, s74
	s_add_i32 s75, s72, 0x6000
	global_load_lds_dwordx4 v210, s[4:5]
	s_mov_b32 m0, s75
	s_cmp_eq_u32 s38, 1
	global_load_lds_dwordx4 v212, s[4:5]
	s_movk_i32 s42, 0x1000
	s_cselect_b64 s[4:5], -1, 0
	s_cmp_lg_u32 s38, 1
	v_readlane_b32 s65, v254, 10
	s_cbranch_scc1 .LBB0_229
	s_setprio 1
	s_barrier

; #define PG8_STAGE(bufoff, gbase, voff) do { _Pragma("unroll") for (int _i = 0; _i < 2; ++_i) \
;         __builtin_amdgcn_global_load_lds((const unsigned*)((const char*)(gbase) + (voff)[_i]), (LAS unsigned*)(lds + (bufoff) + ldsw + _i * 8192), 16, 0, 0); } while (0)
; #define PG8_LDA(dst, b, h) do { _Pragma("unroll") for (int m = 0; m < 4; ++m) _Pragma("unroll") for (int k = 0; k < 2; ++k) dst[m][k] = *(const LAS bf16x8*)(lds + PG8_SA(b, h) + aoff + m * 2048 + k * 1024); } while (0)
; #define PG8_LDB(dst, b, h) do { _Pragma("unroll") for (int n = 0; n < 2; ++n) _Pragma("unroll") for (int k = 0; k < 2; ++k) dst[n][k] = *(const LAS bf16x8*)(lds + PG8_SB(b, h) + boff + n * 2048 + k * 1024); } while (0)
; #define PG8_MMA(ai, bj, At, Bt) do { __builtin_amdgcn_s_setprio(1); _Pragma("unroll") for (int m = 0; m < 4; ++m) _Pragma("unroll") for (int n = 0; n < 2; ++n) _Pragma("unroll") for (int k = 0; k < 2; ++k) \
;         acc[ai][bj][m][n] = __builtin_amdgcn_mfma_f32_16x16x32_bf16(Bt[n][k], At[m][k], acc[ai][bj][m][n], 0, 0, 0); __builtin_amdgcn_s_setprio(0); } while (0)
; #define PG8_WAIT_V(n) asm volatile("s_waitcnt vmcnt(" #n ")" ::: "memory")
; #define PG8_WAIT_L(n) asm volatile("s_waitcnt lgkmcnt(" #n ")" ::: "memory")
; #define PG8_BAR __builtin_amdgcn_s_barrier()
; #define PG8_SCHED __builtin_amdgcn_sched_barrier(0)
; template <class Epi, bool ALIGN_EPI = true>
; __device__ __forceinline__ void gemm_phase(LAS unsigned char* lds, const Gemm g, const Order& S, const Epi& E) {
;     ...
;             const char* a1 = cA + (size_t)(t + 1) * kstepA;
;             const char* a2 = last ? nA : cA + (size_t)(t + 2) * kstepA; const char* b2 = last ? nB : cB + (size_t)(t + 2) * kstepB;
;             const char* a3 = a2 + kstepA; const char* b3 = b2 + kstepB;
;             PG8_LDB(B0, 0, 0); PG8_LDB(B1, 0, 1); PG8_SCHED; PG8_LDA(At, 0, 0); PG8_STAGE(PG8_SA(1, 1), a1 + hstepA, voffA);
;             PG8_WAIT_V(8); PG8_WAIT_L(0); PG8_BAR; PG8_MMA(0, 0, At, B0); PG8_MMA(0, 1, At, B1); PG8_BAR; PG8_SCHED;
;             PG8_LDA(At, 0, 1); PG8_STAGE(PG8_SB(0, 0), b2, voffB); PG8_STAGE(PG8_SB(0, 1), b2 + hstepB, voffB); PG8_STAGE(PG8_SA(0, 0), a2, voffA);
;             PG8_WAIT_V(8); PG8_WAIT_L(0); PG8_BAR; PG8_MMA(1, 0, At, B0); PG8_MMA(1, 1, At, B1); PG8_BAR; PG8_SCHED;
.LBB0_242:
	s_add_i32 s91, s60, 2
	s_add_u32 s61, s58, 0x4000
	s_addc_u32 s62, s59, 0
	s_cmp_eq_u32 s88, s60
	s_cselect_b32 s64, s55, s61
	s_cselect_b32 s65, s47, s62
	s_cselect_b32 s62, s57, s89
	s_cselect_b32 s63, s45, s90
	s_add_u32 s60, s64, 0x8000
	s_addc_u32 s61, s65, 0
	s_add_i32 s92, 0, 0x10000
	s_add_i32 s94, 0, 0x14000
	v_add_u32_e32 v78, s92, v232
	v_add_u32_e32 v94, s94, v232
	ds_read_b128 v[62:65], v78
	ds_read_b128 v[66:69], v78 offset:1024
	ds_read_b128 v[74:77], v78 offset:2048
	ds_read_b128 v[78:81], v78 offset:3072
	ds_read_b128 v[82:85], v94
	ds_read_b128 v[86:89], v94 offset:1024
	ds_read_b128 v[90:93], v94 offset:2048
	ds_read_b128 v[94:97], v94 offset:3072
	v_lshl_add_u64 v[194:195], s[58:59], 0, v[210:211]
	s_add_i32 m0, s72, 0xc000
	ds_read_b128 v[98:101], v208
	ds_read_b128 v[102:105], v208 offset:1024
	ds_read_b128 v[106:109], v208 offset:2048
	ds_read_b128 v[110:113], v208 offset:3072
	ds_read_b128 v[178:181], v208 offset:4096
	ds_read_b128 v[182:185], v208 offset:5120
	ds_read_b128 v[186:189], v208 offset:6144
	ds_read_b128 v[190:193], v208 offset:7168
	global_load_lds_dwordx4 v[194:195], off
	v_lshl_add_u64 v[194:195], s[58:59], 0, v[212:213]
	s_add_i32 m0, s72, 0xe000
	s_nop 0
	global_load_lds_dwordx4 v[194:195], off
	s_waitcnt vmcnt(8)
	s_waitcnt lgkmcnt(0)
	s_barrier
	s_waitcnt lgkmcnt(0)
	v_mfma_f32_16x16x32_bf16 v[174:177], v[62:65], v[98:101], v[174:177]
	v_mfma_f32_16x16x32_bf16 v[170:173], v[74:77], v[98:101], v[170:173]
	v_mfma_f32_16x16x32_bf16 v[158:161], v[62:65], v[106:109], v[158:161]
	v_mfma_f32_16x16x32_bf16 v[154:157], v[74:77], v[106:109], v[154:157]
	v_mfma_f32_16x16x32_bf16 v[142:145], v[62:65], v[178:181], v[142:145]
	v_mfma_f32_16x16x32_bf16 v[138:141], v[74:77], v[178:181], v[138:141]
	v_mfma_f32_16x16x32_bf16 v[126:129], v[62:65], v[186:189], v[126:129]
	v_mfma_f32_16x16x32_bf16 v[122:125], v[74:77], v[186:189], v[122:125]
	v_mfma_f32_16x16x32_bf16 v[174:177], v[66:69], v[102:105], v[174:177]
	v_mfma_f32_16x16x32_bf16 v[170:173], v[78:81], v[102:105], v[170:173]
	v_mfma_f32_16x16x32_bf16 v[158:161], v[66:69], v[110:113], v[158:161]
	v_mfma_f32_16x16x32_bf16 v[154:157], v[78:81], v[110:113], v[154:157]
	v_mfma_f32_16x16x32_bf16 v[142:145], v[66:69], v[182:185], v[142:145]
	v_mfma_f32_16x16x32_bf16 v[138:141], v[78:81], v[182:185], v[138:141]
	v_mfma_f32_16x16x32_bf16 v[126:129], v[66:69], v[190:193], v[126:129]
	v_mfma_f32_16x16x32_bf16 v[122:125], v[78:81], v[190:193], v[122:125]
	v_mfma_f32_16x16x32_bf16 v[166:169], v[82:85], v[98:101], v[166:169]
	v_mfma_f32_16x16x32_bf16 v[98:101], v[90:93], v[98:101], v[162:165]
	v_mfma_f32_16x16x32_bf16 v[166:169], v[86:89], v[102:105], v[166:169]
	v_mfma_f32_16x16x32_bf16 v[98:101], v[94:97], v[102:105], v[98:101]
	v_mfma_f32_16x16x32_bf16 v[102:105], v[82:85], v[106:109], v[150:153]
	v_mfma_f32_16x16x32_bf16 v[106:109], v[90:93], v[106:109], v[146:149]
	v_mfma_f32_16x16x32_bf16 v[130:133], v[90:93], v[178:181], v[130:133]
	v_mfma_f32_16x16x32_bf16 v[118:121], v[82:85], v[186:189], v[118:121]
	v_mfma_f32_16x16x32_bf16 v[114:117], v[90:93], v[186:189], v[114:117]
	v_mfma_f32_16x16x32_bf16 v[102:105], v[86:89], v[110:113], v[102:105]
	v_mfma_f32_16x16x32_bf16 v[106:109], v[94:97], v[110:113], v[106:109]
	v_mfma_f32_16x16x32_bf16 v[110:113], v[82:85], v[178:181], v[134:137]
	v_mfma_f32_16x16x32_bf16 v[130:133], v[94:97], v[182:185], v[130:133]
	v_mfma_f32_16x16x32_bf16 v[118:121], v[86:89], v[190:193], v[118:121]
	v_mfma_f32_16x16x32_bf16 v[114:117], v[94:97], v[190:193], v[114:117]
	v_mfma_f32_16x16x32_bf16 v[110:113], v[86:89], v[182:185], v[110:113]
	s_barrier
	s_add_i32 s92, s92, s71
	v_lshl_add_u64 v[194:195], s[62:63], 0, v[210:211]
	s_mov_b32 m0, s92
	ds_read_b128 v[134:137], v208 offset:16384
	ds_read_b128 v[146:149], v208 offset:17408
	ds_read_b128 v[150:153], v208 offset:18432
	ds_read_b128 v[162:165], v208 offset:19456
	ds_read_b128 v[178:181], v208 offset:20480
	ds_read_b128 v[182:185], v208 offset:21504
	ds_read_b128 v[186:189], v208 offset:22528
	ds_read_b128 v[190:193], v208 offset:23552
	global_load_lds_dwordx4 v[194:195], off
	s_add_i32 m0, s92, 0x2000
	s_add_u32 s92, s62, 0x4000
	v_lshl_add_u64 v[194:195], s[62:63], 0, v[212:213]
	s_addc_u32 s93, s63, 0
	s_add_i32 s94, s94, s71
	global_load_lds_dwordx4 v[194:195], off
	v_lshl_add_u64 v[194:195], s[92:93], 0, v[210:211]
	s_mov_b32 m0, s94
	s_nop 0
	global_load_lds_dwordx4 v[194:195], off
	v_lshl_add_u64 v[194:195], s[92:93], 0, v[212:213]
	s_add_i32 m0, s94, 0x2000
	s_nop 0
	global_load_lds_dwordx4 v[194:195], off
	v_lshl_add_u64 v[194:195], s[64:65], 0, v[210:211]
	s_mov_b32 m0, s72
	s_nop 0
	global_load_lds_dwordx4 v[194:195], off
	v_lshl_add_u64 v[194:195], s[64:65], 0, v[212:213]
	s_mov_b32 m0, s73
	s_nop 0
	global_load_lds_dwordx4 v[194:195], off
	s_waitcnt vmcnt(8)
	s_waitcnt lgkmcnt(0)
	s_barrier
; #define PG8_STAGE(bufoff, gbase, voff) do { _Pragma("unroll") for (int _i = 0; _i < 2; ++_i) \
;         __builtin_amdgcn_global_load_lds((const unsigned*)((const char*)(gbase) + (voff)[_i]), (LAS unsigned*)(lds + (bufoff) + ldsw + _i * 8192), 16, 0, 0); } while (0)
; #define PG8_LDA(dst, b, h) do { _Pragma("unroll") for (int m = 0; m < 4; ++m) _Pragma("unroll") for (int k = 0; k < 2; ++k) dst[m][k] = *(const LAS bf16x8*)(lds + PG8_SA(b, h) + aoff + m * 2048 + k * 1024); } while (0)
; #define PG8_LDB(dst, b, h) do { _Pragma("unroll") for (int n = 0; n < 2; ++n) _Pragma("unroll") for (int k = 0; k < 2; ++k) dst[n][k] = *(const LAS bf16x8*)(lds + PG8_SB(b, h) + boff + n * 2048 + k * 1024); } while (0)
; #define PG8_MMA(ai, bj, At, Bt) do { __builtin_amdgcn_s_setprio(1); _Pragma("unroll") for (int m = 0; m < 4; ++m) _Pragma("unroll") for (int n = 0; n < 2; ++n) _Pragma("unroll") for (int k = 0; k < 2; ++k) \
;         acc[ai][bj][m][n] = __builtin_amdgcn_mfma_f32_16x16x32_bf16(Bt[n][k], At[m][k], acc[ai][bj][m][n], 0, 0, 0); __builtin_amdgcn_s_setprio(0); } while (0)
; #define PG8_WAIT_V(n) asm volatile("s_waitcnt vmcnt(" #n ")" ::: "memory")
; #define PG8_WAIT_L(n) asm volatile("s_waitcnt lgkmcnt(" #n ")" ::: "memory")
; #define PG8_BAR __builtin_amdgcn_s_barrier()
; #define PG8_SCHED __builtin_amdgcn_sched_barrier(0)
; template <class Epi, bool ALIGN_EPI = true>
; __device__ __forceinline__ void gemm_phase(LAS unsigned char* lds, const Gemm g, const Order& S, const Epi& E) {
;     ...
;             PG8_WAIT_V(8); PG8_WAIT_L(0); PG8_BAR; PG8_MMA(1, 0, At, B0); PG8_MMA(1, 1, At, B1); PG8_BAR; PG8_SCHED;
;             PG8_LDB(B0, 1, 0); PG8_LDB(B1, 1, 1); PG8_SCHED; PG8_LDA(At, 1, 0); PG8_STAGE(PG8_SA(0, 1), a2 + hstepA, voffA);
;             PG8_WAIT_V(8); PG8_WAIT_L(0); PG8_BAR; PG8_MMA(0, 0, At, B0); PG8_MMA(0, 1, At, B1); PG8_BAR; PG8_SCHED;
	s_waitcnt lgkmcnt(0)
	v_mfma_f32_16x16x32_bf16 v[70:73], v[62:65], v[134:137], v[70:73]
	v_mfma_f32_16x16x32_bf16 v[58:61], v[74:77], v[134:137], v[58:61]
	v_mfma_f32_16x16x32_bf16 v[46:49], v[62:65], v[150:153], v[46:49]
	v_mfma_f32_16x16x32_bf16 v[42:45], v[74:77], v[150:153], v[42:45]
	v_mfma_f32_16x16x32_bf16 v[30:33], v[62:65], v[178:181], v[30:33]
	v_mfma_f32_16x16x32_bf16 v[26:29], v[74:77], v[178:181], v[26:29]
	v_mfma_f32_16x16x32_bf16 v[14:17], v[62:65], v[186:189], v[14:17]
	v_mfma_f32_16x16x32_bf16 v[10:13], v[74:77], v[186:189], v[10:13]
	v_mfma_f32_16x16x32_bf16 v[70:73], v[66:69], v[146:149], v[70:73]
	v_mfma_f32_16x16x32_bf16 v[58:61], v[78:81], v[146:149], v[58:61]
	v_mfma_f32_16x16x32_bf16 v[46:49], v[66:69], v[162:165], v[46:49]
	v_mfma_f32_16x16x32_bf16 v[42:45], v[78:81], v[162:165], v[42:45]
	v_mfma_f32_16x16x32_bf16 v[30:33], v[66:69], v[182:185], v[30:33]
	v_mfma_f32_16x16x32_bf16 v[26:29], v[78:81], v[182:185], v[26:29]
	v_mfma_f32_16x16x32_bf16 v[14:17], v[66:69], v[190:193], v[14:17]
	v_mfma_f32_16x16x32_bf16 v[10:13], v[78:81], v[190:193], v[10:13]
	v_mfma_f32_16x16x32_bf16 v[54:57], v[82:85], v[134:137], v[54:57]
	v_mfma_f32_16x16x32_bf16 v[50:53], v[90:93], v[134:137], v[50:53]
	v_mfma_f32_16x16x32_bf16 v[38:41], v[82:85], v[150:153], v[38:41]
	v_mfma_f32_16x16x32_bf16 v[34:37], v[90:93], v[150:153], v[34:37]
	v_mfma_f32_16x16x32_bf16 v[22:25], v[82:85], v[178:181], v[22:25]
	v_mfma_f32_16x16x32_bf16 v[18:21], v[90:93], v[178:181], v[18:21]
	v_mfma_f32_16x16x32_bf16 v[6:9], v[82:85], v[186:189], v[6:9]
	v_mfma_f32_16x16x32_bf16 v[2:5], v[90:93], v[186:189], v[2:5]
	v_mfma_f32_16x16x32_bf16 v[54:57], v[86:89], v[146:149], v[54:57]
	v_mfma_f32_16x16x32_bf16 v[50:53], v[94:97], v[146:149], v[50:53]
	v_mfma_f32_16x16x32_bf16 v[38:41], v[86:89], v[162:165], v[38:41]
	v_mfma_f32_16x16x32_bf16 v[34:37], v[94:97], v[162:165], v[34:37]
	v_mfma_f32_16x16x32_bf16 v[22:25], v[86:89], v[182:185], v[22:25]
	v_mfma_f32_16x16x32_bf16 v[18:21], v[94:97], v[182:185], v[18:21]
	v_mfma_f32_16x16x32_bf16 v[6:9], v[86:89], v[190:193], v[6:9]
	v_mfma_f32_16x16x32_bf16 v[2:5], v[94:97], v[190:193], v[2:5]
	s_barrier
	s_add_i32 s92, 0, 0x18000
	s_add_i32 s93, 0, 0x1c000
	v_add_u32_e32 v78, s92, v232
	v_add_u32_e32 v94, s93, v232
	ds_read_b128 v[62:65], v78
	ds_read_b128 v[66:69], v78 offset:1024
	ds_read_b128 v[74:77], v78 offset:2048
	ds_read_b128 v[78:81], v78 offset:3072
	ds_read_b128 v[82:85], v94
	ds_read_b128 v[86:89], v94 offset:1024
	ds_read_b128 v[90:93], v94 offset:2048
	ds_read_b128 v[94:97], v94 offset:3072
	s_add_u32 s64, s64, 0x4000
	s_addc_u32 s65, s65, 0
	s_mov_b32 m0, s74
	v_lshl_add_u64 v[150:151], s[64:65], 0, v[210:211]
	ds_read_b128 v[134:137], v208 offset:32768
	ds_read_b128 v[146:149], v208 offset:33792
	ds_read_b128 v[178:181], v208 offset:34816
	ds_read_b128 v[182:185], v208 offset:35840
	ds_read_b128 v[186:189], v208 offset:36864
	ds_read_b128 v[190:193], v208 offset:37888
	ds_read_b128 v[194:197], v208 offset:38912
	ds_read_b128 v[198:201], v208 offset:39936
	global_load_lds_dwordx4 v[150:151], off
	v_lshl_add_u64 v[150:151], s[64:65], 0, v[212:213]
	s_mov_b32 m0, s75
	s_nop 0
	global_load_lds_dwordx4 v[150:151], off
	s_waitcnt vmcnt(8)
	s_waitcnt lgkmcnt(0)
	s_barrier
	s_waitcnt lgkmcnt(0)
	v_mfma_f32_16x16x32_bf16 v[150:153], v[62:65], v[134:137], v[174:177]
	v_mfma_f32_16x16x32_bf16 v[174:177], v[66:69], v[146:149], v[150:153]
	v_mfma_f32_16x16x32_bf16 v[150:153], v[74:77], v[134:137], v[170:173]
	v_mfma_f32_16x16x32_bf16 v[170:173], v[78:81], v[146:149], v[150:153]
	v_mfma_f32_16x16x32_bf16 v[150:153], v[62:65], v[178:181], v[158:161]
	v_mfma_f32_16x16x32_bf16 v[158:161], v[66:69], v[182:185], v[150:153]
	v_mfma_f32_16x16x32_bf16 v[150:153], v[74:77], v[178:181], v[154:157]
	v_mfma_f32_16x16x32_bf16 v[142:145], v[62:65], v[186:189], v[142:145]
	v_mfma_f32_16x16x32_bf16 v[138:141], v[74:77], v[186:189], v[138:141]
	v_mfma_f32_16x16x32_bf16 v[126:129], v[62:65], v[194:197], v[126:129]
	v_mfma_f32_16x16x32_bf16 v[122:125], v[74:77], v[194:197], v[122:125]
	v_mfma_f32_16x16x32_bf16 v[154:157], v[78:81], v[182:185], v[150:153]
	v_mfma_f32_16x16x32_bf16 v[142:145], v[66:69], v[190:193], v[142:145]
	v_mfma_f32_16x16x32_bf16 v[138:141], v[78:81], v[190:193], v[138:141]
	v_mfma_f32_16x16x32_bf16 v[126:129], v[66:69], v[198:201], v[126:129]
	v_mfma_f32_16x16x32_bf16 v[122:125], v[78:81], v[198:201], v[122:125]
	v_mfma_f32_16x16x32_bf16 v[98:101], v[90:93], v[134:137], v[98:101]
	v_mfma_f32_16x16x32_bf16 v[150:153], v[82:85], v[134:137], v[166:169]
	v_mfma_f32_16x16x32_bf16 v[162:165], v[94:97], v[146:149], v[98:101]
	v_mfma_f32_16x16x32_bf16 v[98:101], v[82:85], v[178:181], v[102:105]
	v_mfma_f32_16x16x32_bf16 v[166:169], v[86:89], v[146:149], v[150:153]
	v_mfma_f32_16x16x32_bf16 v[150:153], v[86:89], v[182:185], v[98:101]
	v_mfma_f32_16x16x32_bf16 v[98:101], v[90:93], v[178:181], v[106:109]
	v_mfma_f32_16x16x32_bf16 v[146:149], v[94:97], v[182:185], v[98:101]
	v_mfma_f32_16x16x32_bf16 v[98:101], v[82:85], v[186:189], v[110:113]
	v_mfma_f32_16x16x32_bf16 v[134:137], v[86:89], v[190:193], v[98:101]
	v_mfma_f32_16x16x32_bf16 v[98:101], v[90:93], v[186:189], v[130:133]
	v_mfma_f32_16x16x32_bf16 v[130:133], v[94:97], v[190:193], v[98:101]
	v_mfma_f32_16x16x32_bf16 v[98:101], v[82:85], v[194:197], v[118:121]
	v_mfma_f32_16x16x32_bf16 v[118:121], v[86:89], v[198:201], v[98:101]
	v_mfma_f32_16x16x32_bf16 v[98:101], v[90:93], v[194:197], v[114:117]
	v_mfma_f32_16x16x32_bf16 v[114:117], v[94:97], v[198:201], v[98:101]
	s_barrier
; #define PG8_STAGE(bufoff, gbase, voff) do { _Pragma("unroll") for (int _i = 0; _i < 2; ++_i) \
;         __builtin_amdgcn_global_load_lds((const unsigned*)((const char*)(gbase) + (voff)[_i]), (LAS unsigned*)(lds + (bufoff) + ldsw + _i * 8192), 16, 0, 0); } while (0)
; #define PG8_LDA(dst, b, h) do { _Pragma("unroll") for (int m = 0; m < 4; ++m) _Pragma("unroll") for (int k = 0; k < 2; ++k) dst[m][k] = *(const LAS bf16x8*)(lds + PG8_SA(b, h) + aoff + m * 2048 + k * 1024); } while (0)
; #define PG8_MMA(ai, bj, At, Bt) do { __builtin_amdgcn_s_setprio(1); _Pragma("unroll") for (int m = 0; m < 4; ++m) _Pragma("unroll") for (int n = 0; n < 2; ++n) _Pragma("unroll") for (int k = 0; k < 2; ++k) \
;         acc[ai][bj][m][n] = __builtin_amdgcn_mfma_f32_16x16x32_bf16(Bt[n][k], At[m][k], acc[ai][bj][m][n], 0, 0, 0); __builtin_amdgcn_s_setprio(0); } while (0)
; #define PG8_WAIT_V(n) asm volatile("s_waitcnt vmcnt(" #n ")" ::: "memory")
; #define PG8_WAIT_L(n) asm volatile("s_waitcnt lgkmcnt(" #n ")" ::: "memory")
; #define PG8_BAR __builtin_amdgcn_s_barrier()
; #define PG8_SCHED __builtin_amdgcn_sched_barrier(0)
; template <class Epi, bool ALIGN_EPI = true>
; __device__ __forceinline__ void gemm_phase(LAS unsigned char* lds, const Gemm g, const Order& S, const Epi& E) {
;     ...
;             PG8_LDA(At, 1, 1); PG8_STAGE(PG8_SB(1, 0), b3, voffB); PG8_STAGE(PG8_SB(1, 1), b3 + hstepB, voffB); PG8_STAGE(PG8_SA(1, 0), a3, voffA);
;             PG8_WAIT_V(8); PG8_WAIT_L(0); PG8_BAR; PG8_MMA(1, 0, At, B0); PG8_MMA(1, 1, At, B1); PG8_BAR; PG8_SCHED;
;         }
;         if constexpr (ALIGN_EPI) { if (wr == 0) PG8_BAR; }
	s_add_u32 s64, s62, 0x8000
	s_addc_u32 s65, s63, 0
	s_add_i32 s92, s92, s71
	v_lshl_add_u64 v[194:195], s[64:65], 0, v[210:211]
	s_mov_b32 m0, s92
	ds_read_b128 v[98:101], v208 offset:49152
	ds_read_b128 v[102:105], v208 offset:50176
	ds_read_b128 v[106:109], v208 offset:51200
	ds_read_b128 v[110:113], v208 offset:52224
	ds_read_b128 v[178:181], v208 offset:53248
	ds_read_b128 v[182:185], v208 offset:54272
	ds_read_b128 v[186:189], v208 offset:55296
	ds_read_b128 v[190:193], v208 offset:56320
	global_load_lds_dwordx4 v[194:195], off
	s_add_i32 m0, s92, 0x2000
	s_add_u32 s62, s62, 0xc000
	v_lshl_add_u64 v[194:195], s[64:65], 0, v[212:213]
	s_addc_u32 s63, s63, 0
	s_add_i32 s64, s93, s71
	global_load_lds_dwordx4 v[194:195], off
	v_lshl_add_u64 v[194:195], s[62:63], 0, v[210:211]
	s_mov_b32 m0, s64
	s_nop 0
	global_load_lds_dwordx4 v[194:195], off
	v_lshl_add_u64 v[194:195], s[62:63], 0, v[212:213]
	s_add_i32 m0, s64, 0x2000
	s_nop 0
	global_load_lds_dwordx4 v[194:195], off
	v_lshl_add_u64 v[194:195], s[60:61], 0, v[210:211]
	s_mov_b32 m0, s79
	s_nop 0
	global_load_lds_dwordx4 v[194:195], off
	v_lshl_add_u64 v[194:195], s[60:61], 0, v[212:213]
	s_mov_b32 m0, s80
	s_nop 0
	global_load_lds_dwordx4 v[194:195], off
	s_waitcnt vmcnt(8)
	s_waitcnt lgkmcnt(0)
	s_barrier
	s_waitcnt lgkmcnt(0)
	v_mfma_f32_16x16x32_bf16 v[70:73], v[62:65], v[98:101], v[70:73]
	v_mfma_f32_16x16x32_bf16 v[58:61], v[74:77], v[98:101], v[58:61]
	v_mfma_f32_16x16x32_bf16 v[46:49], v[62:65], v[106:109], v[46:49]
	v_mfma_f32_16x16x32_bf16 v[42:45], v[74:77], v[106:109], v[42:45]
	v_mfma_f32_16x16x32_bf16 v[30:33], v[62:65], v[178:181], v[30:33]
	v_mfma_f32_16x16x32_bf16 v[26:29], v[74:77], v[178:181], v[26:29]
	v_mfma_f32_16x16x32_bf16 v[14:17], v[62:65], v[186:189], v[14:17]
	v_mfma_f32_16x16x32_bf16 v[10:13], v[74:77], v[186:189], v[10:13]
	v_mfma_f32_16x16x32_bf16 v[70:73], v[66:69], v[102:105], v[70:73]
	v_mfma_f32_16x16x32_bf16 v[58:61], v[78:81], v[102:105], v[58:61]
	v_mfma_f32_16x16x32_bf16 v[46:49], v[66:69], v[110:113], v[46:49]
	v_mfma_f32_16x16x32_bf16 v[42:45], v[78:81], v[110:113], v[42:45]
	v_mfma_f32_16x16x32_bf16 v[30:33], v[66:69], v[182:185], v[30:33]
	v_mfma_f32_16x16x32_bf16 v[26:29], v[78:81], v[182:185], v[26:29]
	v_mfma_f32_16x16x32_bf16 v[14:17], v[66:69], v[190:193], v[14:17]
	v_mfma_f32_16x16x32_bf16 v[10:13], v[78:81], v[190:193], v[10:13]
	v_mfma_f32_16x16x32_bf16 v[54:57], v[82:85], v[98:101], v[54:57]
	v_mfma_f32_16x16x32_bf16 v[50:53], v[90:93], v[98:101], v[50:53]
	v_mfma_f32_16x16x32_bf16 v[38:41], v[82:85], v[106:109], v[38:41]
	v_mfma_f32_16x16x32_bf16 v[34:37], v[90:93], v[106:109], v[34:37]
	v_mfma_f32_16x16x32_bf16 v[22:25], v[82:85], v[178:181], v[22:25]
	v_mfma_f32_16x16x32_bf16 v[18:21], v[90:93], v[178:181], v[18:21]
	v_mfma_f32_16x16x32_bf16 v[6:9], v[82:85], v[186:189], v[6:9]
	v_mfma_f32_16x16x32_bf16 v[2:5], v[90:93], v[186:189], v[2:5]
	v_mfma_f32_16x16x32_bf16 v[54:57], v[86:89], v[102:105], v[54:57]
	v_mfma_f32_16x16x32_bf16 v[50:53], v[94:97], v[102:105], v[50:53]
	v_mfma_f32_16x16x32_bf16 v[38:41], v[86:89], v[110:113], v[38:41]
	v_mfma_f32_16x16x32_bf16 v[34:37], v[94:97], v[110:113], v[34:37]
	v_mfma_f32_16x16x32_bf16 v[22:25], v[86:89], v[182:185], v[22:25]
	v_mfma_f32_16x16x32_bf16 v[18:21], v[94:97], v[182:185], v[18:21]
	v_mfma_f32_16x16x32_bf16 v[6:9], v[86:89], v[190:193], v[6:9]
	v_mfma_f32_16x16x32_bf16 v[2:5], v[94:97], v[190:193], v[2:5]
	s_barrier
	s_add_u32 s58, s58, 0x10000
	s_addc_u32 s59, s59, 0
	s_add_u32 s89, s89, 0x10000
	s_addc_u32 s90, s90, 0
	s_cmp_ge_u32 s91, s86
	s_mov_b32 s60, s91
	s_cbranch_scc0 .LBB0_242
	s_and_b64 vcc, exec, s[40:41]
	s_cbranch_vccz .LBB0_245
	s_barrier

; #define PG8_STAGE(bufoff, gbase, voff) do { _Pragma("unroll") for (int _i = 0; _i < 2; ++_i) \
;         __builtin_amdgcn_global_load_lds((const unsigned*)((const char*)(gbase) + (voff)[_i]), (LAS unsigned*)(lds + (bufoff) + ldsw + _i * 8192), 16, 0, 0); } while (0)
; #define PG8_BAR __builtin_amdgcn_s_barrier()
; template <class Epi, bool ALIGN_EPI = true>
; __device__ __forceinline__ void gemm_phase(LAS unsigned char* lds, const Gemm g, const Order& S, const Epi& E) {
;     ...
;     const char* cA = (const char*)g.A + (size_t)cur.pm * tstepA + (size_t)(cur.k0 >> 6) * kstepA; const char* cB = (const char*)g.Bt + (size_t)cur.pn * tstepB + (size_t)(cur.k0 >> 6) * kstepB;
;     PG8_STAGE(PG8_SB(0, 0), cB, voffB); PG8_STAGE(PG8_SB(0, 1), cB + hstepB, voffB); PG8_STAGE(PG8_SA(0, 0), cA, voffA); PG8_STAGE(PG8_SA(0, 1), cA + hstepA, voffA);
;     if constexpr (Epi::PRELOAD) { E.preload(pre, S, tid); __syncthreads(); }
;     if (wr == 1) PG8_BAR;
; __global__ void __launch_bounds__(NTHREADS, 2) fwd(Args a) {
;     ...
;             const float* tab = (const float*)(a.ws + WS_TAB) + (size_t)(2 * l) * 15 * DM;
;             pg8::Gemm g{(const bf16_t*)(a.ws + WS_MIX), (const bf16_t*)(wl + WT_OUT), DM, 64, DM, slab, (size_t)256 * 64 * 2, (size_t)256 * DM * 2};
;             pg8::Order S; S.init(64, 4, G, bx, lastl ? 0 : 16 * 4, 64, DM / 64, 4);
;             pg8::EpiRes E{(bf16_t*)(a.ws + WS_XG), ss, tab};
;             pg8::gemm_phase<pg8::EpiRes>(lds, g, S, E);
.LBB0_358:
	v_readlane_b32 s8, v255, 18
	s_mov_b32 s54, s28
	s_lshl_b32 s38, s8, 1
	s_mul_i32 s39, s8, 0x1e000
	v_readlane_b32 s28, v252, 30
	s_mul_hi_i32 s38, s38, 0xf000
	v_readlane_b32 s29, v252, 31
	s_add_u32 s64, s28, s39
	s_addc_u32 s65, s29, s38
	s_andn2_b64 vcc, exec, s[36:37]
	v_readlane_b32 s9, v255, 19
	s_cbranch_vccnz .LBB0_402
	s_add_u32 s67, s10, 0x380000
	s_addc_u32 s68, s90, 0
	s_ashr_i32 s37, s1, 6
	s_ashr_i32 s55, s54, 31
	s_ashr_i32 s36, s1, 8
	s_lshl_b32 s69, s37, 10
	s_lshl_b64 s[38:39], s[54:55], 19
	v_readlane_b32 s28, v253, 18
	v_readlane_b32 s29, v253, 19
	s_add_u32 s40, s28, s38
	s_addc_u32 s41, s29, s39
	s_ashr_i32 s53, s52, 31
	s_lshl_b64 s[38:39], s[52:53], 19
	s_add_u32 s38, s67, s38
	s_addc_u32 s39, s68, s39
	s_add_u32 s58, s38, s4
	s_addc_u32 s59, s39, s5
	s_add_i32 s70, s69, 0
	v_lshlrev_b32_e32 v210, 4, v2
	s_add_i32 m0, s70, 0x10000
	v_add_u32_e32 v212, 0x2000, v210
	global_load_lds_dwordx4 v210, s[58:59]
	s_add_i32 m0, s70, 0x12000
	s_add_u32 s38, s58, 0x4000
	global_load_lds_dwordx4 v212, s[58:59]
	s_addc_u32 s39, s59, 0
	s_add_i32 m0, s70, 0x14000
	v_writelane_b32 v255, s57, 20
	global_load_lds_dwordx4 v210, s[38:39]
	s_add_i32 m0, s70, 0x16000
	s_add_u32 s56, s40, s4
	s_addc_u32 s57, s41, s5
	s_add_i32 s71, s70, 0x2000
	global_load_lds_dwordx4 v212, s[38:39]
	s_mov_b32 m0, s70
	s_add_u32 s4, s56, 0x4000
	global_load_lds_dwordx4 v210, s[56:57]
	s_mov_b32 m0, s71
	s_addc_u32 s5, s57, 0
	s_add_i32 s72, s70, 0x4000
	global_load_lds_dwordx4 v212, s[56:57]
	s_mov_b32 m0, s72
	s_add_i32 s73, s70, 0x6000
	global_load_lds_dwordx4 v210, s[4:5]
	s_mov_b32 m0, s73
	s_cmp_eq_u32 s36, 1
	global_load_lds_dwordx4 v212, s[4:5]
	v_readlane_b32 s62, v254, 9
	s_movk_i32 s42, 0x1000
	s_cselect_b64 s[4:5], -1, 0
	s_cmp_lg_u32 s36, 1
	v_readlane_b32 s63, v254, 10
	s_cbranch_scc1 .LBB0_361
	s_setprio 1
	s_barrier

; #define PG8_STAGE(bufoff, gbase, voff) do { _Pragma("unroll") for (int _i = 0; _i < 2; ++_i) \
;         __builtin_amdgcn_global_load_lds((const unsigned*)((const char*)(gbase) + (voff)[_i]), (LAS unsigned*)(lds + (bufoff) + ldsw + _i * 8192), 16, 0, 0); } while (0)
; #define PG8_LDA(dst, b, h) do { _Pragma("unroll") for (int m = 0; m < 4; ++m) _Pragma("unroll") for (int k = 0; k < 2; ++k) dst[m][k] = *(const LAS bf16x8*)(lds + PG8_SA(b, h) + aoff + m * 2048 + k * 1024); } while (0)
; #define PG8_LDB(dst, b, h) do { _Pragma("unroll") for (int n = 0; n < 2; ++n) _Pragma("unroll") for (int k = 0; k < 2; ++k) dst[n][k] = *(const LAS bf16x8*)(lds + PG8_SB(b, h) + boff + n * 2048 + k * 1024); } while (0)
; #define PG8_MMA(ai, bj, At, Bt) do { __builtin_amdgcn_s_setprio(1); _Pragma("unroll") for (int m = 0; m < 4; ++m) _Pragma("unroll") for (int n = 0; n < 2; ++n) _Pragma("unroll") for (int k = 0; k < 2; ++k) \
;         acc[ai][bj][m][n] = __builtin_amdgcn_mfma_f32_16x16x32_bf16(Bt[n][k], At[m][k], acc[ai][bj][m][n], 0, 0, 0); __builtin_amdgcn_s_setprio(0); } while (0)
; #define PG8_WAIT_V(n) asm volatile("s_waitcnt vmcnt(" #n ")" ::: "memory")
; #define PG8_WAIT_L(n) asm volatile("s_waitcnt lgkmcnt(" #n ")" ::: "memory")
; #define PG8_BAR __builtin_amdgcn_s_barrier()
; #define PG8_SCHED __builtin_amdgcn_sched_barrier(0)
; template <class Epi, bool ALIGN_EPI = true>
; __device__ __forceinline__ void gemm_phase(LAS unsigned char* lds, const Gemm g, const Order& S, const Epi& E) {
;     ...
;             const char* a1 = cA + (size_t)(t + 1) * kstepA;
;             const char* a2 = last ? nA : cA + (size_t)(t + 2) * kstepA; const char* b2 = last ? nB : cB + (size_t)(t + 2) * kstepB;
;             const char* a3 = a2 + kstepA; const char* b3 = b2 + kstepB;
;             PG8_LDB(B0, 0, 0); PG8_LDB(B1, 0, 1); PG8_SCHED; PG8_LDA(At, 0, 0); PG8_STAGE(PG8_SA(1, 1), a1 + hstepA, voffA);
;             PG8_WAIT_V(8); PG8_WAIT_L(0); PG8_BAR; PG8_MMA(0, 0, At, B0); PG8_MMA(0, 1, At, B1); PG8_BAR; PG8_SCHED;
;             PG8_LDA(At, 0, 1); PG8_STAGE(PG8_SB(0, 0), b2, voffB); PG8_STAGE(PG8_SB(0, 1), b2 + hstepB, voffB); PG8_STAGE(PG8_SA(0, 0), a2, voffA);
;             PG8_WAIT_V(8); PG8_WAIT_L(0); PG8_BAR; PG8_MMA(1, 0, At, B0); PG8_MMA(1, 1, At, B1); PG8_BAR; PG8_SCHED;
.LBB0_374:
	s_add_i32 s89, s58, 2
	s_add_u32 s59, s56, 0x4000
	s_addc_u32 s60, s57, 0
	s_cmp_eq_u32 s86, s58
	s_cselect_b32 s62, s53, s59
	s_cselect_b32 s63, s45, s60
	s_cselect_b32 s60, s55, s87
	s_cselect_b32 s61, s41, s88
	s_add_u32 s58, s62, 0x8000
	s_addc_u32 s59, s63, 0
	s_add_i32 s90, 0, 0x10000
	s_add_i32 s92, 0, 0x14000
	v_add_u32_e32 v78, s90, v232
	v_add_u32_e32 v94, s92, v232
	ds_read_b128 v[62:65], v78
	ds_read_b128 v[66:69], v78 offset:1024
	ds_read_b128 v[74:77], v78 offset:2048
	ds_read_b128 v[78:81], v78 offset:3072
	ds_read_b128 v[82:85], v94
	ds_read_b128 v[86:89], v94 offset:1024
	ds_read_b128 v[90:93], v94 offset:2048
	ds_read_b128 v[94:97], v94 offset:3072
	v_lshl_add_u64 v[194:195], s[56:57], 0, v[210:211]
	s_add_i32 m0, s70, 0xc000
	ds_read_b128 v[98:101], v209
	ds_read_b128 v[102:105], v209 offset:1024
	ds_read_b128 v[106:109], v209 offset:2048
	ds_read_b128 v[110:113], v209 offset:3072
	ds_read_b128 v[178:181], v209 offset:4096
	ds_read_b128 v[182:185], v209 offset:5120
	ds_read_b128 v[186:189], v209 offset:6144
	ds_read_b128 v[190:193], v209 offset:7168
	global_load_lds_dwordx4 v[194:195], off
	v_lshl_add_u64 v[194:195], s[56:57], 0, v[212:213]
	s_add_i32 m0, s70, 0xe000
	s_nop 0
	global_load_lds_dwordx4 v[194:195], off
	s_waitcnt vmcnt(8)
	s_waitcnt lgkmcnt(0)
	s_barrier
	s_waitcnt lgkmcnt(0)
	v_mfma_f32_16x16x32_bf16 v[174:177], v[62:65], v[98:101], v[174:177]
	v_mfma_f32_16x16x32_bf16 v[170:173], v[74:77], v[98:101], v[170:173]
	v_mfma_f32_16x16x32_bf16 v[158:161], v[62:65], v[106:109], v[158:161]
	v_mfma_f32_16x16x32_bf16 v[154:157], v[74:77], v[106:109], v[154:157]
	v_mfma_f32_16x16x32_bf16 v[142:145], v[62:65], v[178:181], v[142:145]
	v_mfma_f32_16x16x32_bf16 v[138:141], v[74:77], v[178:181], v[138:141]
	v_mfma_f32_16x16x32_bf16 v[126:129], v[62:65], v[186:189], v[126:129]
	v_mfma_f32_16x16x32_bf16 v[122:125], v[74:77], v[186:189], v[122:125]
	v_mfma_f32_16x16x32_bf16 v[174:177], v[66:69], v[102:105], v[174:177]
	v_mfma_f32_16x16x32_bf16 v[170:173], v[78:81], v[102:105], v[170:173]
	v_mfma_f32_16x16x32_bf16 v[158:161], v[66:69], v[110:113], v[158:161]
	v_mfma_f32_16x16x32_bf16 v[154:157], v[78:81], v[110:113], v[154:157]
	v_mfma_f32_16x16x32_bf16 v[142:145], v[66:69], v[182:185], v[142:145]
	v_mfma_f32_16x16x32_bf16 v[138:141], v[78:81], v[182:185], v[138:141]
	v_mfma_f32_16x16x32_bf16 v[126:129], v[66:69], v[190:193], v[126:129]
	v_mfma_f32_16x16x32_bf16 v[122:125], v[78:81], v[190:193], v[122:125]
	v_mfma_f32_16x16x32_bf16 v[166:169], v[82:85], v[98:101], v[166:169]
	v_mfma_f32_16x16x32_bf16 v[98:101], v[90:93], v[98:101], v[162:165]
	v_mfma_f32_16x16x32_bf16 v[166:169], v[86:89], v[102:105], v[166:169]
	v_mfma_f32_16x16x32_bf16 v[98:101], v[94:97], v[102:105], v[98:101]
	v_mfma_f32_16x16x32_bf16 v[102:105], v[82:85], v[106:109], v[150:153]
	v_mfma_f32_16x16x32_bf16 v[106:109], v[90:93], v[106:109], v[146:149]
	v_mfma_f32_16x16x32_bf16 v[130:133], v[90:93], v[178:181], v[130:133]
	v_mfma_f32_16x16x32_bf16 v[118:121], v[82:85], v[186:189], v[118:121]
	v_mfma_f32_16x16x32_bf16 v[114:117], v[90:93], v[186:189], v[114:117]
	v_mfma_f32_16x16x32_bf16 v[102:105], v[86:89], v[110:113], v[102:105]
	v_mfma_f32_16x16x32_bf16 v[106:109], v[94:97], v[110:113], v[106:109]
	v_mfma_f32_16x16x32_bf16 v[110:113], v[82:85], v[178:181], v[134:137]
	v_mfma_f32_16x16x32_bf16 v[130:133], v[94:97], v[182:185], v[130:133]
	v_mfma_f32_16x16x32_bf16 v[118:121], v[86:89], v[190:193], v[118:121]
	v_mfma_f32_16x16x32_bf16 v[114:117], v[94:97], v[190:193], v[114:117]
	v_mfma_f32_16x16x32_bf16 v[110:113], v[86:89], v[182:185], v[110:113]
	s_barrier
	s_add_i32 s90, s90, s69
	v_lshl_add_u64 v[194:195], s[60:61], 0, v[210:211]
	s_mov_b32 m0, s90
	ds_read_b128 v[134:137], v209 offset:16384
	ds_read_b128 v[146:149], v209 offset:17408
	ds_read_b128 v[150:153], v209 offset:18432
	ds_read_b128 v[162:165], v209 offset:19456
	ds_read_b128 v[178:181], v209 offset:20480
	ds_read_b128 v[182:185], v209 offset:21504
	ds_read_b128 v[186:189], v209 offset:22528
	ds_read_b128 v[190:193], v209 offset:23552
	global_load_lds_dwordx4 v[194:195], off
	s_add_i32 m0, s90, 0x2000
	s_add_u32 s90, s60, 0x4000
	v_lshl_add_u64 v[194:195], s[60:61], 0, v[212:213]
	s_addc_u32 s91, s61, 0
	s_add_i32 s92, s92, s69
	global_load_lds_dwordx4 v[194:195], off
	v_lshl_add_u64 v[194:195], s[90:91], 0, v[210:211]
	s_mov_b32 m0, s92
	s_nop 0
	global_load_lds_dwordx4 v[194:195], off
	v_lshl_add_u64 v[194:195], s[90:91], 0, v[212:213]
	s_add_i32 m0, s92, 0x2000
	s_nop 0
	global_load_lds_dwordx4 v[194:195], off
	v_lshl_add_u64 v[194:195], s[62:63], 0, v[210:211]
	s_mov_b32 m0, s70
	s_nop 0
	global_load_lds_dwordx4 v[194:195], off
	v_lshl_add_u64 v[194:195], s[62:63], 0, v[212:213]
	s_mov_b32 m0, s71
	s_nop 0
	global_load_lds_dwordx4 v[194:195], off
	s_waitcnt vmcnt(8)
	s_waitcnt lgkmcnt(0)
	s_barrier
; #define PG8_STAGE(bufoff, gbase, voff) do { _Pragma("unroll") for (int _i = 0; _i < 2; ++_i) \
;         __builtin_amdgcn_global_load_lds((const unsigned*)((const char*)(gbase) + (voff)[_i]), (LAS unsigned*)(lds + (bufoff) + ldsw + _i * 8192), 16, 0, 0); } while (0)
; #define PG8_LDA(dst, b, h) do { _Pragma("unroll") for (int m = 0; m < 4; ++m) _Pragma("unroll") for (int k = 0; k < 2; ++k) dst[m][k] = *(const LAS bf16x8*)(lds + PG8_SA(b, h) + aoff + m * 2048 + k * 1024); } while (0)
; #define PG8_LDB(dst, b, h) do { _Pragma("unroll") for (int n = 0; n < 2; ++n) _Pragma("unroll") for (int k = 0; k < 2; ++k) dst[n][k] = *(const LAS bf16x8*)(lds + PG8_SB(b, h) + boff + n * 2048 + k * 1024); } while (0)
; #define PG8_MMA(ai, bj, At, Bt) do { __builtin_amdgcn_s_setprio(1); _Pragma("unroll") for (int m = 0; m < 4; ++m) _Pragma("unroll") for (int n = 0; n < 2; ++n) _Pragma("unroll") for (int k = 0; k < 2; ++k) \
;         acc[ai][bj][m][n] = __builtin_amdgcn_mfma_f32_16x16x32_bf16(Bt[n][k], At[m][k], acc[ai][bj][m][n], 0, 0, 0); __builtin_amdgcn_s_setprio(0); } while (0)
; #define PG8_WAIT_V(n) asm volatile("s_waitcnt vmcnt(" #n ")" ::: "memory")
; #define PG8_WAIT_L(n) asm volatile("s_waitcnt lgkmcnt(" #n ")" ::: "memory")
; #define PG8_BAR __builtin_amdgcn_s_barrier()
; #define PG8_SCHED __builtin_amdgcn_sched_barrier(0)
; template <class Epi, bool ALIGN_EPI = true>
; __device__ __forceinline__ void gemm_phase(LAS unsigned char* lds, const Gemm g, const Order& S, const Epi& E) {
;     ...
;             PG8_WAIT_V(8); PG8_WAIT_L(0); PG8_BAR; PG8_MMA(1, 0, At, B0); PG8_MMA(1, 1, At, B1); PG8_BAR; PG8_SCHED;
;             PG8_LDB(B0, 1, 0); PG8_LDB(B1, 1, 1); PG8_SCHED; PG8_LDA(At, 1, 0); PG8_STAGE(PG8_SA(0, 1), a2 + hstepA, voffA);
;             PG8_WAIT_V(8); PG8_WAIT_L(0); PG8_BAR; PG8_MMA(0, 0, At, B0); PG8_MMA(0, 1, At, B1); PG8_BAR; PG8_SCHED;
	s_waitcnt lgkmcnt(0)
	v_mfma_f32_16x16x32_bf16 v[70:73], v[62:65], v[134:137], v[70:73]
	v_mfma_f32_16x16x32_bf16 v[58:61], v[74:77], v[134:137], v[58:61]
	v_mfma_f32_16x16x32_bf16 v[46:49], v[62:65], v[150:153], v[46:49]
	v_mfma_f32_16x16x32_bf16 v[42:45], v[74:77], v[150:153], v[42:45]
	v_mfma_f32_16x16x32_bf16 v[30:33], v[62:65], v[178:181], v[30:33]
	v_mfma_f32_16x16x32_bf16 v[26:29], v[74:77], v[178:181], v[26:29]
	v_mfma_f32_16x16x32_bf16 v[14:17], v[62:65], v[186:189], v[14:17]
	v_mfma_f32_16x16x32_bf16 v[10:13], v[74:77], v[186:189], v[10:13]
	v_mfma_f32_16x16x32_bf16 v[70:73], v[66:69], v[146:149], v[70:73]
	v_mfma_f32_16x16x32_bf16 v[58:61], v[78:81], v[146:149], v[58:61]
	v_mfma_f32_16x16x32_bf16 v[46:49], v[66:69], v[162:165], v[46:49]
	v_mfma_f32_16x16x32_bf16 v[42:45], v[78:81], v[162:165], v[42:45]
	v_mfma_f32_16x16x32_bf16 v[30:33], v[66:69], v[182:185], v[30:33]
	v_mfma_f32_16x16x32_bf16 v[26:29], v[78:81], v[182:185], v[26:29]
	v_mfma_f32_16x16x32_bf16 v[14:17], v[66:69], v[190:193], v[14:17]
	v_mfma_f32_16x16x32_bf16 v[10:13], v[78:81], v[190:193], v[10:13]
	v_mfma_f32_16x16x32_bf16 v[54:57], v[82:85], v[134:137], v[54:57]
	v_mfma_f32_16x16x32_bf16 v[50:53], v[90:93], v[134:137], v[50:53]
	v_mfma_f32_16x16x32_bf16 v[38:41], v[82:85], v[150:153], v[38:41]
	v_mfma_f32_16x16x32_bf16 v[34:37], v[90:93], v[150:153], v[34:37]
	v_mfma_f32_16x16x32_bf16 v[22:25], v[82:85], v[178:181], v[22:25]
	v_mfma_f32_16x16x32_bf16 v[18:21], v[90:93], v[178:181], v[18:21]
	v_mfma_f32_16x16x32_bf16 v[6:9], v[82:85], v[186:189], v[6:9]
	v_mfma_f32_16x16x32_bf16 v[2:5], v[90:93], v[186:189], v[2:5]
	v_mfma_f32_16x16x32_bf16 v[54:57], v[86:89], v[146:149], v[54:57]
	v_mfma_f32_16x16x32_bf16 v[50:53], v[94:97], v[146:149], v[50:53]
	v_mfma_f32_16x16x32_bf16 v[38:41], v[86:89], v[162:165], v[38:41]
	v_mfma_f32_16x16x32_bf16 v[34:37], v[94:97], v[162:165], v[34:37]
	v_mfma_f32_16x16x32_bf16 v[22:25], v[86:89], v[182:185], v[22:25]
	v_mfma_f32_16x16x32_bf16 v[18:21], v[94:97], v[182:185], v[18:21]
	v_mfma_f32_16x16x32_bf16 v[6:9], v[86:89], v[190:193], v[6:9]
	v_mfma_f32_16x16x32_bf16 v[2:5], v[94:97], v[190:193], v[2:5]
	s_barrier
	s_add_i32 s90, 0, 0x18000
	s_add_i32 s91, 0, 0x1c000
	v_add_u32_e32 v78, s90, v232
	v_add_u32_e32 v94, s91, v232
	ds_read_b128 v[62:65], v78
	ds_read_b128 v[66:69], v78 offset:1024
	ds_read_b128 v[74:77], v78 offset:2048
	ds_read_b128 v[78:81], v78 offset:3072
	ds_read_b128 v[82:85], v94
	ds_read_b128 v[86:89], v94 offset:1024
	ds_read_b128 v[90:93], v94 offset:2048
	ds_read_b128 v[94:97], v94 offset:3072
	s_add_u32 s62, s62, 0x4000
	s_addc_u32 s63, s63, 0
	s_mov_b32 m0, s72
	v_lshl_add_u64 v[150:151], s[62:63], 0, v[210:211]
	ds_read_b128 v[134:137], v209 offset:32768
	ds_read_b128 v[146:149], v209 offset:33792
	ds_read_b128 v[178:181], v209 offset:34816
	ds_read_b128 v[182:185], v209 offset:35840
	ds_read_b128 v[186:189], v209 offset:36864
	ds_read_b128 v[190:193], v209 offset:37888
	ds_read_b128 v[194:197], v209 offset:38912
	ds_read_b128 v[198:201], v209 offset:39936
	global_load_lds_dwordx4 v[150:151], off
	v_lshl_add_u64 v[150:151], s[62:63], 0, v[212:213]
	s_mov_b32 m0, s73
	s_nop 0
	global_load_lds_dwordx4 v[150:151], off
	s_waitcnt vmcnt(8)
	s_waitcnt lgkmcnt(0)
	s_barrier
	s_waitcnt lgkmcnt(0)
	v_mfma_f32_16x16x32_bf16 v[150:153], v[62:65], v[134:137], v[174:177]
	v_mfma_f32_16x16x32_bf16 v[174:177], v[66:69], v[146:149], v[150:153]
	v_mfma_f32_16x16x32_bf16 v[150:153], v[74:77], v[134:137], v[170:173]
	v_mfma_f32_16x16x32_bf16 v[170:173], v[78:81], v[146:149], v[150:153]
	v_mfma_f32_16x16x32_bf16 v[150:153], v[62:65], v[178:181], v[158:161]
	v_mfma_f32_16x16x32_bf16 v[158:161], v[66:69], v[182:185], v[150:153]
	v_mfma_f32_16x16x32_bf16 v[150:153], v[74:77], v[178:181], v[154:157]
	v_mfma_f32_16x16x32_bf16 v[142:145], v[62:65], v[186:189], v[142:145]
	v_mfma_f32_16x16x32_bf16 v[138:141], v[74:77], v[186:189], v[138:141]
	v_mfma_f32_16x16x32_bf16 v[126:129], v[62:65], v[194:197], v[126:129]
	v_mfma_f32_16x16x32_bf16 v[122:125], v[74:77], v[194:197], v[122:125]
	v_mfma_f32_16x16x32_bf16 v[154:157], v[78:81], v[182:185], v[150:153]
	v_mfma_f32_16x16x32_bf16 v[142:145], v[66:69], v[190:193], v[142:145]
	v_mfma_f32_16x16x32_bf16 v[138:141], v[78:81], v[190:193], v[138:141]
	v_mfma_f32_16x16x32_bf16 v[126:129], v[66:69], v[198:201], v[126:129]
	v_mfma_f32_16x16x32_bf16 v[122:125], v[78:81], v[198:201], v[122:125]
	v_mfma_f32_16x16x32_bf16 v[98:101], v[90:93], v[134:137], v[98:101]
	v_mfma_f32_16x16x32_bf16 v[150:153], v[82:85], v[134:137], v[166:169]
	v_mfma_f32_16x16x32_bf16 v[162:165], v[94:97], v[146:149], v[98:101]
	v_mfma_f32_16x16x32_bf16 v[98:101], v[82:85], v[178:181], v[102:105]
	v_mfma_f32_16x16x32_bf16 v[166:169], v[86:89], v[146:149], v[150:153]
	v_mfma_f32_16x16x32_bf16 v[150:153], v[86:89], v[182:185], v[98:101]
	v_mfma_f32_16x16x32_bf16 v[98:101], v[90:93], v[178:181], v[106:109]
	v_mfma_f32_16x16x32_bf16 v[146:149], v[94:97], v[182:185], v[98:101]
	v_mfma_f32_16x16x32_bf16 v[98:101], v[82:85], v[186:189], v[110:113]
	v_mfma_f32_16x16x32_bf16 v[134:137], v[86:89], v[190:193], v[98:101]
	v_mfma_f32_16x16x32_bf16 v[98:101], v[90:93], v[186:189], v[130:133]
	v_mfma_f32_16x16x32_bf16 v[130:133], v[94:97], v[190:193], v[98:101]
	v_mfma_f32_16x16x32_bf16 v[98:101], v[82:85], v[194:197], v[118:121]
	v_mfma_f32_16x16x32_bf16 v[118:121], v[86:89], v[198:201], v[98:101]
	v_mfma_f32_16x16x32_bf16 v[98:101], v[90:93], v[194:197], v[114:117]
	v_mfma_f32_16x16x32_bf16 v[114:117], v[94:97], v[198:201], v[98:101]
	s_barrier
; #define PG8_STAGE(bufoff, gbase, voff) do { _Pragma("unroll") for (int _i = 0; _i < 2; ++_i) \
;         __builtin_amdgcn_global_load_lds((const unsigned*)((const char*)(gbase) + (voff)[_i]), (LAS unsigned*)(lds + (bufoff) + ldsw + _i * 8192), 16, 0, 0); } while (0)
; #define PG8_LDA(dst, b, h) do { _Pragma("unroll") for (int m = 0; m < 4; ++m) _Pragma("unroll") for (int k = 0; k < 2; ++k) dst[m][k] = *(const LAS bf16x8*)(lds + PG8_SA(b, h) + aoff + m * 2048 + k * 1024); } while (0)
; #define PG8_MMA(ai, bj, At, Bt) do { __builtin_amdgcn_s_setprio(1); _Pragma("unroll") for (int m = 0; m < 4; ++m) _Pragma("unroll") for (int n = 0; n < 2; ++n) _Pragma("unroll") for (int k = 0; k < 2; ++k) \
;         acc[ai][bj][m][n] = __builtin_amdgcn_mfma_f32_16x16x32_bf16(Bt[n][k], At[m][k], acc[ai][bj][m][n], 0, 0, 0); __builtin_amdgcn_s_setprio(0); } while (0)
; #define PG8_WAIT_V(n) asm volatile("s_waitcnt vmcnt(" #n ")" ::: "memory")
; #define PG8_WAIT_L(n) asm volatile("s_waitcnt lgkmcnt(" #n ")" ::: "memory")
; #define PG8_BAR __builtin_amdgcn_s_barrier()
; #define PG8_SCHED __builtin_amdgcn_sched_barrier(0)
; template <class Epi, bool ALIGN_EPI = true>
; __device__ __forceinline__ void gemm_phase(LAS unsigned char* lds, const Gemm g, const Order& S, const Epi& E) {
;     ...
;             PG8_LDA(At, 1, 1); PG8_STAGE(PG8_SB(1, 0), b3, voffB); PG8_STAGE(PG8_SB(1, 1), b3 + hstepB, voffB); PG8_STAGE(PG8_SA(1, 0), a3, voffA);
;             PG8_WAIT_V(8); PG8_WAIT_L(0); PG8_BAR; PG8_MMA(1, 0, At, B0); PG8_MMA(1, 1, At, B1); PG8_BAR; PG8_SCHED;
;         }
;         if constexpr (ALIGN_EPI) { if (wr == 0) PG8_BAR; }
	s_add_u32 s62, s60, 0x8000
	s_addc_u32 s63, s61, 0
	s_add_i32 s90, s90, s69
	v_lshl_add_u64 v[194:195], s[62:63], 0, v[210:211]
	s_mov_b32 m0, s90
	ds_read_b128 v[98:101], v209 offset:49152
	ds_read_b128 v[102:105], v209 offset:50176
	ds_read_b128 v[106:109], v209 offset:51200
	ds_read_b128 v[110:113], v209 offset:52224
	ds_read_b128 v[178:181], v209 offset:53248
	ds_read_b128 v[182:185], v209 offset:54272
	ds_read_b128 v[186:189], v209 offset:55296
	ds_read_b128 v[190:193], v209 offset:56320
	global_load_lds_dwordx4 v[194:195], off
	s_add_i32 m0, s90, 0x2000
	s_add_u32 s60, s60, 0xc000
	v_lshl_add_u64 v[194:195], s[62:63], 0, v[212:213]
	s_addc_u32 s61, s61, 0
	s_add_i32 s62, s91, s69
	global_load_lds_dwordx4 v[194:195], off
	v_lshl_add_u64 v[194:195], s[60:61], 0, v[210:211]
	s_mov_b32 m0, s62
	s_nop 0
	global_load_lds_dwordx4 v[194:195], off
	v_lshl_add_u64 v[194:195], s[60:61], 0, v[212:213]
	s_add_i32 m0, s62, 0x2000
	s_nop 0
	global_load_lds_dwordx4 v[194:195], off
	v_lshl_add_u64 v[194:195], s[58:59], 0, v[210:211]
	s_mov_b32 m0, s77
	s_nop 0
	global_load_lds_dwordx4 v[194:195], off
	v_lshl_add_u64 v[194:195], s[58:59], 0, v[212:213]
	s_mov_b32 m0, s78
	s_nop 0
	global_load_lds_dwordx4 v[194:195], off
	s_waitcnt vmcnt(8)
	s_waitcnt lgkmcnt(0)
	s_barrier
	s_waitcnt lgkmcnt(0)
	v_mfma_f32_16x16x32_bf16 v[70:73], v[62:65], v[98:101], v[70:73]
	v_mfma_f32_16x16x32_bf16 v[58:61], v[74:77], v[98:101], v[58:61]
	v_mfma_f32_16x16x32_bf16 v[46:49], v[62:65], v[106:109], v[46:49]
	v_mfma_f32_16x16x32_bf16 v[42:45], v[74:77], v[106:109], v[42:45]
	v_mfma_f32_16x16x32_bf16 v[30:33], v[62:65], v[178:181], v[30:33]
	v_mfma_f32_16x16x32_bf16 v[26:29], v[74:77], v[178:181], v[26:29]
	v_mfma_f32_16x16x32_bf16 v[14:17], v[62:65], v[186:189], v[14:17]
	v_mfma_f32_16x16x32_bf16 v[10:13], v[74:77], v[186:189], v[10:13]
	v_mfma_f32_16x16x32_bf16 v[70:73], v[66:69], v[102:105], v[70:73]
	v_mfma_f32_16x16x32_bf16 v[58:61], v[78:81], v[102:105], v[58:61]
	v_mfma_f32_16x16x32_bf16 v[46:49], v[66:69], v[110:113], v[46:49]
	v_mfma_f32_16x16x32_bf16 v[42:45], v[78:81], v[110:113], v[42:45]
	v_mfma_f32_16x16x32_bf16 v[30:33], v[66:69], v[182:185], v[30:33]
	v_mfma_f32_16x16x32_bf16 v[26:29], v[78:81], v[182:185], v[26:29]
	v_mfma_f32_16x16x32_bf16 v[14:17], v[66:69], v[190:193], v[14:17]
	v_mfma_f32_16x16x32_bf16 v[10:13], v[78:81], v[190:193], v[10:13]
	v_mfma_f32_16x16x32_bf16 v[54:57], v[82:85], v[98:101], v[54:57]
	v_mfma_f32_16x16x32_bf16 v[50:53], v[90:93], v[98:101], v[50:53]
	v_mfma_f32_16x16x32_bf16 v[38:41], v[82:85], v[106:109], v[38:41]
	v_mfma_f32_16x16x32_bf16 v[34:37], v[90:93], v[106:109], v[34:37]
	v_mfma_f32_16x16x32_bf16 v[22:25], v[82:85], v[178:181], v[22:25]
	v_mfma_f32_16x16x32_bf16 v[18:21], v[90:93], v[178:181], v[18:21]
	v_mfma_f32_16x16x32_bf16 v[6:9], v[82:85], v[186:189], v[6:9]
	v_mfma_f32_16x16x32_bf16 v[2:5], v[90:93], v[186:189], v[2:5]
	v_mfma_f32_16x16x32_bf16 v[54:57], v[86:89], v[102:105], v[54:57]
	v_mfma_f32_16x16x32_bf16 v[50:53], v[94:97], v[102:105], v[50:53]
	v_mfma_f32_16x16x32_bf16 v[38:41], v[86:89], v[110:113], v[38:41]
	v_mfma_f32_16x16x32_bf16 v[34:37], v[94:97], v[110:113], v[34:37]
	v_mfma_f32_16x16x32_bf16 v[22:25], v[86:89], v[182:185], v[22:25]
	v_mfma_f32_16x16x32_bf16 v[18:21], v[94:97], v[182:185], v[18:21]
	v_mfma_f32_16x16x32_bf16 v[6:9], v[86:89], v[190:193], v[6:9]
	v_mfma_f32_16x16x32_bf16 v[2:5], v[94:97], v[190:193], v[2:5]
	s_barrier
	s_add_u32 s56, s56, 0x10000
	s_addc_u32 s57, s57, 0
	s_add_u32 s87, s87, 0x10000
	s_addc_u32 s88, s88, 0
	s_cmp_ge_u32 s89, s84
	s_mov_b32 s58, s89
	s_cbranch_scc0 .LBB0_374
	s_and_b64 vcc, exec, s[38:39]
	s_cbranch_vccz .LBB0_377
	s_barrier

; #define PG8_WAIT_V(n) asm volatile("s_waitcnt vmcnt(" #n ")" ::: "memory")
; #define PG8_BAR __builtin_amdgcn_s_barrier()
; template <class Epi, bool ALIGN_EPI = true>
; __device__ __forceinline__ void gemm_phase(LAS unsigned char* lds, const Gemm g, const Order& S, const Epi& E) {
;     ...
;     if constexpr (Epi::PRELOAD) { E.preload(pre, S, tid); __syncthreads(); }
;     if (wr == 1) PG8_BAR;
;     PG8_WAIT_V(2); PG8_BAR;
.LBB0_879:
	s_or_b64 exec, exec, s[36:37]
	s_ashr_i32 s34, s48, 8
	s_cmp_eq_u32 s34, 1
	s_cselect_b64 s[36:37], -1, 0
	s_cmp_lg_u32 s34, 1
	s_waitcnt vmcnt(0)
	ds_write2st64_b32 v99, v104, v105 offset0:32 offset1:40
	s_waitcnt lgkmcnt(0)
	s_barrier
	s_cbranch_scc1 .LBB0_881
	s_setprio 1
	s_barrier

; #define PG8_STAGE(bufoff, gbase, voff) do { _Pragma("unroll") for (int _i = 0; _i < 2; ++_i) \
;         __builtin_amdgcn_global_load_lds((const unsigned*)((const char*)(gbase) + (voff)[_i]), (LAS unsigned*)(lds + (bufoff) + ldsw + _i * 8192), 16, 0, 0); } while (0)
; #define PG8_LDA(dst, b, h) do { _Pragma("unroll") for (int m = 0; m < 4; ++m) _Pragma("unroll") for (int k = 0; k < 2; ++k) dst[m][k] = *(const LAS bf16x8*)(lds + PG8_SA(b, h) + aoff + m * 2048 + k * 1024); } while (0)
; #define PG8_LDB(dst, b, h) do { _Pragma("unroll") for (int n = 0; n < 2; ++n) _Pragma("unroll") for (int k = 0; k < 2; ++k) dst[n][k] = *(const LAS bf16x8*)(lds + PG8_SB(b, h) + boff + n * 2048 + k * 1024); } while (0)
; #define PG8_MMA(ai, bj, At, Bt) do { __builtin_amdgcn_s_setprio(1); _Pragma("unroll") for (int m = 0; m < 4; ++m) _Pragma("unroll") for (int n = 0; n < 2; ++n) _Pragma("unroll") for (int k = 0; k < 2; ++k) \
;         acc[ai][bj][m][n] = __builtin_amdgcn_mfma_f32_16x16x32_bf16(Bt[n][k], At[m][k], acc[ai][bj][m][n], 0, 0, 0); __builtin_amdgcn_s_setprio(0); } while (0)
; #define PG8_WAIT_V(n) asm volatile("s_waitcnt vmcnt(" #n ")" ::: "memory")
; #define PG8_WAIT_L(n) asm volatile("s_waitcnt lgkmcnt(" #n ")" ::: "memory")
; #define PG8_BAR __builtin_amdgcn_s_barrier()
; #define PG8_SCHED __builtin_amdgcn_sched_barrier(0)
; template <class Epi, bool ALIGN_EPI = true>
; __device__ __forceinline__ void gemm_phase(LAS unsigned char* lds, const Gemm g, const Order& S, const Epi& E) {
;     ...
;             const char* a1 = cA + (size_t)(t + 1) * kstepA;
;             const char* a2 = last ? nA : cA + (size_t)(t + 2) * kstepA; const char* b2 = last ? nB : cB + (size_t)(t + 2) * kstepB;
;             const char* a3 = a2 + kstepA; const char* b3 = b2 + kstepB;
;             PG8_LDB(B0, 0, 0); PG8_LDB(B1, 0, 1); PG8_SCHED; PG8_LDA(At, 0, 0); PG8_STAGE(PG8_SA(1, 1), a1 + hstepA, voffA);
;             PG8_WAIT_V(8); PG8_WAIT_L(0); PG8_BAR; PG8_MMA(0, 0, At, B0); PG8_MMA(0, 1, At, B1); PG8_BAR; PG8_SCHED;
;             PG8_LDA(At, 0, 1); PG8_STAGE(PG8_SB(0, 0), b2, voffB); PG8_STAGE(PG8_SB(0, 1), b2 + hstepB, voffB); PG8_STAGE(PG8_SA(0, 0), a2, voffA);
;             PG8_WAIT_V(8); PG8_WAIT_L(0); PG8_BAR; PG8_MMA(1, 0, At, B0); PG8_MMA(1, 1, At, B1); PG8_BAR; PG8_SCHED;
.LBB0_893:
	s_add_u32 s58, s40, s52
	s_addc_u32 s59, s41, s53
	s_add_u32 s58, s58, 0x10000
	s_addc_u32 s59, s59, 0
	s_add_u32 s60, s80, s52
	s_addc_u32 s61, s81, s53
	s_cmp_eq_u32 s52, 0x70000
	s_cselect_b32 s62, s35, s58
	s_cselect_b32 s63, s34, s59
	s_cselect_b32 s60, s47, s60
	s_cselect_b32 s61, s45, s61
	s_add_u32 s58, s62, 0x8000
	s_addc_u32 s59, s63, 0
	s_add_i32 s83, 0, 0x10000
	s_add_i32 s86, 0, 0x14000
	v_add_u32_e32 v146, s83, v173
	v_add_u32_e32 v166, s86, v173
	ds_read_b128 v[134:137], v146
	ds_read_b128 v[138:141], v146 offset:1024
	ds_read_b128 v[142:145], v146 offset:2048
	ds_read_b128 v[146:149], v146 offset:3072
	ds_read_b128 v[150:153], v166
	ds_read_b128 v[154:157], v166 offset:1024
	ds_read_b128 v[162:165], v166 offset:2048
	ds_read_b128 v[184:187], v166 offset:3072
	v_lshl_add_u64 v[204:205], v[130:131], 0, s[52:53]
	s_add_i32 m0, s5, 0xc000
	ds_read_b128 v[188:191], v183
	ds_read_b128 v[192:195], v183 offset:1024
	ds_read_b128 v[196:199], v183 offset:2048
	ds_read_b128 v[200:203], v183 offset:3072
	ds_read_b128 v[208:211], v183 offset:4096
	ds_read_b128 v[212:215], v183 offset:5120
	ds_read_b128 v[216:219], v183 offset:6144
	ds_read_b128 v[230:233], v183 offset:7168
	global_load_lds_dwordx4 v[204:205], off
	v_lshl_add_u64 v[204:205], v[132:133], 0, s[52:53]
	s_add_i32 m0, s5, 0xe000
	s_nop 0
	global_load_lds_dwordx4 v[204:205], off
	s_waitcnt vmcnt(8)
	s_waitcnt lgkmcnt(0)
	s_barrier
	s_waitcnt lgkmcnt(0)
	v_mfma_f32_16x16x32_bf16 v[126:129], v[134:137], v[188:191], v[126:129]
	v_mfma_f32_16x16x32_bf16 v[122:125], v[142:145], v[188:191], v[122:125]
	v_mfma_f32_16x16x32_bf16 v[118:121], v[134:137], v[196:199], v[118:121]
	v_mfma_f32_16x16x32_bf16 v[114:117], v[142:145], v[196:199], v[114:117]
	v_mfma_f32_16x16x32_bf16 v[110:113], v[134:137], v[208:211], v[110:113]
	v_mfma_f32_16x16x32_bf16 v[106:109], v[142:145], v[208:211], v[106:109]
	v_mfma_f32_16x16x32_bf16 v[102:105], v[134:137], v[216:219], v[102:105]
	v_mfma_f32_16x16x32_bf16 v[98:101], v[142:145], v[216:219], v[98:101]
	v_mfma_f32_16x16x32_bf16 v[126:129], v[138:141], v[192:195], v[126:129]
	v_mfma_f32_16x16x32_bf16 v[122:125], v[146:149], v[192:195], v[122:125]
	v_mfma_f32_16x16x32_bf16 v[118:121], v[138:141], v[200:203], v[118:121]
	v_mfma_f32_16x16x32_bf16 v[114:117], v[146:149], v[200:203], v[114:117]
	v_mfma_f32_16x16x32_bf16 v[110:113], v[138:141], v[212:215], v[110:113]
	v_mfma_f32_16x16x32_bf16 v[106:109], v[146:149], v[212:215], v[106:109]
	v_mfma_f32_16x16x32_bf16 v[102:105], v[138:141], v[230:233], v[102:105]
	v_mfma_f32_16x16x32_bf16 v[98:101], v[146:149], v[230:233], v[98:101]
	v_mfma_f32_16x16x32_bf16 v[94:97], v[150:153], v[188:191], v[94:97]
	v_mfma_f32_16x16x32_bf16 v[90:93], v[162:165], v[188:191], v[90:93]
	v_mfma_f32_16x16x32_bf16 v[86:89], v[150:153], v[196:199], v[86:89]
	v_mfma_f32_16x16x32_bf16 v[82:85], v[162:165], v[196:199], v[82:85]
	v_mfma_f32_16x16x32_bf16 v[78:81], v[150:153], v[208:211], v[78:81]
	v_mfma_f32_16x16x32_bf16 v[74:77], v[162:165], v[208:211], v[74:77]
	v_mfma_f32_16x16x32_bf16 v[70:73], v[150:153], v[216:219], v[70:73]
	v_mfma_f32_16x16x32_bf16 v[66:69], v[162:165], v[216:219], v[66:69]
	v_mfma_f32_16x16x32_bf16 v[94:97], v[154:157], v[192:195], v[94:97]
	v_mfma_f32_16x16x32_bf16 v[90:93], v[184:187], v[192:195], v[90:93]
	v_mfma_f32_16x16x32_bf16 v[86:89], v[154:157], v[200:203], v[86:89]
	v_mfma_f32_16x16x32_bf16 v[82:85], v[184:187], v[200:203], v[82:85]
	v_mfma_f32_16x16x32_bf16 v[78:81], v[154:157], v[212:215], v[78:81]
	v_mfma_f32_16x16x32_bf16 v[74:77], v[184:187], v[212:215], v[74:77]
	v_mfma_f32_16x16x32_bf16 v[70:73], v[154:157], v[230:233], v[70:73]
	v_mfma_f32_16x16x32_bf16 v[66:69], v[184:187], v[230:233], v[66:69]
	s_barrier
	s_add_i32 s83, s83, s65
	v_lshl_add_u64 v[204:205], s[60:61], 0, v[206:207]
	s_mov_b32 m0, s83
	ds_read_b128 v[188:191], v183 offset:16384
	ds_read_b128 v[192:195], v183 offset:17408
	ds_read_b128 v[196:199], v183 offset:18432
	ds_read_b128 v[200:203], v183 offset:19456
	ds_read_b128 v[208:211], v183 offset:20480
	ds_read_b128 v[212:215], v183 offset:21504
	ds_read_b128 v[216:219], v183 offset:22528
	ds_read_b128 v[230:233], v183 offset:23552
	global_load_lds_dwordx4 v[204:205], off
	s_add_i32 m0, s83, 0x2000
	s_add_u32 s84, s60, 0x4000
	v_lshl_add_u64 v[204:205], s[60:61], 0, v[158:159]
	s_addc_u32 s85, s61, 0
	s_add_i32 s83, s86, s65
	global_load_lds_dwordx4 v[204:205], off
	v_lshl_add_u64 v[204:205], s[84:85], 0, v[206:207]
	s_mov_b32 m0, s83
	s_nop 0
	global_load_lds_dwordx4 v[204:205], off
	v_lshl_add_u64 v[204:205], s[84:85], 0, v[158:159]
	s_add_i32 m0, s83, 0x2000
	s_nop 0
	global_load_lds_dwordx4 v[204:205], off
	v_lshl_add_u64 v[204:205], s[62:63], 0, v[206:207]
	s_mov_b32 m0, s5
	s_nop 0
	global_load_lds_dwordx4 v[204:205], off
	v_lshl_add_u64 v[204:205], s[62:63], 0, v[158:159]
	s_mov_b32 m0, s39
	s_nop 0
	global_load_lds_dwordx4 v[204:205], off
	s_waitcnt vmcnt(8)
	s_waitcnt lgkmcnt(0)
	s_barrier
; #define PG8_STAGE(bufoff, gbase, voff) do { _Pragma("unroll") for (int _i = 0; _i < 2; ++_i) \
;         __builtin_amdgcn_global_load_lds((const unsigned*)((const char*)(gbase) + (voff)[_i]), (LAS unsigned*)(lds + (bufoff) + ldsw + _i * 8192), 16, 0, 0); } while (0)
; #define PG8_LDA(dst, b, h) do { _Pragma("unroll") for (int m = 0; m < 4; ++m) _Pragma("unroll") for (int k = 0; k < 2; ++k) dst[m][k] = *(const LAS bf16x8*)(lds + PG8_SA(b, h) + aoff + m * 2048 + k * 1024); } while (0)
; #define PG8_LDB(dst, b, h) do { _Pragma("unroll") for (int n = 0; n < 2; ++n) _Pragma("unroll") for (int k = 0; k < 2; ++k) dst[n][k] = *(const LAS bf16x8*)(lds + PG8_SB(b, h) + boff + n * 2048 + k * 1024); } while (0)
; #define PG8_MMA(ai, bj, At, Bt) do { __builtin_amdgcn_s_setprio(1); _Pragma("unroll") for (int m = 0; m < 4; ++m) _Pragma("unroll") for (int n = 0; n < 2; ++n) _Pragma("unroll") for (int k = 0; k < 2; ++k) \
;         acc[ai][bj][m][n] = __builtin_amdgcn_mfma_f32_16x16x32_bf16(Bt[n][k], At[m][k], acc[ai][bj][m][n], 0, 0, 0); __builtin_amdgcn_s_setprio(0); } while (0)
; #define PG8_WAIT_V(n) asm volatile("s_waitcnt vmcnt(" #n ")" ::: "memory")
; #define PG8_WAIT_L(n) asm volatile("s_waitcnt lgkmcnt(" #n ")" ::: "memory")
; #define PG8_BAR __builtin_amdgcn_s_barrier()
; #define PG8_SCHED __builtin_amdgcn_sched_barrier(0)
; template <class Epi, bool ALIGN_EPI = true>
; __device__ __forceinline__ void gemm_phase(LAS unsigned char* lds, const Gemm g, const Order& S, const Epi& E) {
;     ...
;             PG8_WAIT_V(8); PG8_WAIT_L(0); PG8_BAR; PG8_MMA(1, 0, At, B0); PG8_MMA(1, 1, At, B1); PG8_BAR; PG8_SCHED;
;             PG8_LDB(B0, 1, 0); PG8_LDB(B1, 1, 1); PG8_SCHED; PG8_LDA(At, 1, 0); PG8_STAGE(PG8_SA(0, 1), a2 + hstepA, voffA);
;             PG8_WAIT_V(8); PG8_WAIT_L(0); PG8_BAR; PG8_MMA(0, 0, At, B0); PG8_MMA(0, 1, At, B1); PG8_BAR; PG8_SCHED;
	s_waitcnt lgkmcnt(0)
	v_mfma_f32_16x16x32_bf16 v[62:65], v[134:137], v[188:191], v[62:65]
	v_mfma_f32_16x16x32_bf16 v[58:61], v[142:145], v[188:191], v[58:61]
	v_mfma_f32_16x16x32_bf16 v[54:57], v[134:137], v[196:199], v[54:57]
	v_mfma_f32_16x16x32_bf16 v[50:53], v[142:145], v[196:199], v[50:53]
	v_mfma_f32_16x16x32_bf16 v[46:49], v[134:137], v[208:211], v[46:49]
	v_mfma_f32_16x16x32_bf16 v[42:45], v[142:145], v[208:211], v[42:45]
	v_mfma_f32_16x16x32_bf16 v[38:41], v[134:137], v[216:219], v[38:41]
	v_mfma_f32_16x16x32_bf16 v[34:37], v[142:145], v[216:219], v[34:37]
	v_mfma_f32_16x16x32_bf16 v[62:65], v[138:141], v[192:195], v[62:65]
	v_mfma_f32_16x16x32_bf16 v[58:61], v[146:149], v[192:195], v[58:61]
	v_mfma_f32_16x16x32_bf16 v[54:57], v[138:141], v[200:203], v[54:57]
	v_mfma_f32_16x16x32_bf16 v[50:53], v[146:149], v[200:203], v[50:53]
	v_mfma_f32_16x16x32_bf16 v[46:49], v[138:141], v[212:215], v[46:49]
	v_mfma_f32_16x16x32_bf16 v[42:45], v[146:149], v[212:215], v[42:45]
	v_mfma_f32_16x16x32_bf16 v[38:41], v[138:141], v[230:233], v[38:41]
	v_mfma_f32_16x16x32_bf16 v[34:37], v[146:149], v[230:233], v[34:37]
	v_mfma_f32_16x16x32_bf16 v[30:33], v[150:153], v[188:191], v[30:33]
	v_mfma_f32_16x16x32_bf16 v[26:29], v[162:165], v[188:191], v[26:29]
	v_mfma_f32_16x16x32_bf16 v[22:25], v[150:153], v[196:199], v[22:25]
	v_mfma_f32_16x16x32_bf16 v[18:21], v[162:165], v[196:199], v[18:21]
	v_mfma_f32_16x16x32_bf16 v[14:17], v[150:153], v[208:211], v[14:17]
	v_mfma_f32_16x16x32_bf16 v[10:13], v[162:165], v[208:211], v[10:13]
	v_mfma_f32_16x16x32_bf16 v[6:9], v[150:153], v[216:219], v[6:9]
	v_mfma_f32_16x16x32_bf16 v[2:5], v[162:165], v[216:219], v[2:5]
	v_mfma_f32_16x16x32_bf16 v[30:33], v[154:157], v[192:195], v[30:33]
	v_mfma_f32_16x16x32_bf16 v[26:29], v[184:187], v[192:195], v[26:29]
	v_mfma_f32_16x16x32_bf16 v[22:25], v[154:157], v[200:203], v[22:25]
	v_mfma_f32_16x16x32_bf16 v[18:21], v[184:187], v[200:203], v[18:21]
	v_mfma_f32_16x16x32_bf16 v[14:17], v[154:157], v[212:215], v[14:17]
	v_mfma_f32_16x16x32_bf16 v[10:13], v[184:187], v[212:215], v[10:13]
	v_mfma_f32_16x16x32_bf16 v[6:9], v[154:157], v[230:233], v[6:9]
	v_mfma_f32_16x16x32_bf16 v[2:5], v[184:187], v[230:233], v[2:5]
	s_barrier
	s_add_i32 s83, 0, 0x18000
	s_add_i32 s84, 0, 0x1c000
	v_add_u32_e32 v146, s83, v173
	v_add_u32_e32 v166, s84, v173
	ds_read_b128 v[134:137], v146
	ds_read_b128 v[138:141], v146 offset:1024
	ds_read_b128 v[142:145], v146 offset:2048
	ds_read_b128 v[146:149], v146 offset:3072
	ds_read_b128 v[150:153], v166
	ds_read_b128 v[154:157], v166 offset:1024
	ds_read_b128 v[162:165], v166 offset:2048
	ds_read_b128 v[184:187], v166 offset:3072
	s_add_u32 s62, s62, 0x4000
	s_addc_u32 s63, s63, 0
	s_mov_b32 m0, s66
	v_lshl_add_u64 v[204:205], s[62:63], 0, v[206:207]
	ds_read_b128 v[188:191], v183 offset:32768
	ds_read_b128 v[192:195], v183 offset:33792
	ds_read_b128 v[196:199], v183 offset:34816
	ds_read_b128 v[200:203], v183 offset:35840
	ds_read_b128 v[208:211], v183 offset:36864
	ds_read_b128 v[212:215], v183 offset:37888
	ds_read_b128 v[216:219], v183 offset:38912
	ds_read_b128 v[230:233], v183 offset:39936
	global_load_lds_dwordx4 v[204:205], off
	v_lshl_add_u64 v[204:205], s[62:63], 0, v[158:159]
	s_mov_b32 m0, s67
	s_nop 0
	global_load_lds_dwordx4 v[204:205], off
	s_waitcnt vmcnt(8)
	s_waitcnt lgkmcnt(0)
	s_barrier
	s_waitcnt lgkmcnt(0)
	v_mfma_f32_16x16x32_bf16 v[126:129], v[134:137], v[188:191], v[126:129]
	v_mfma_f32_16x16x32_bf16 v[122:125], v[142:145], v[188:191], v[122:125]
	v_mfma_f32_16x16x32_bf16 v[118:121], v[134:137], v[196:199], v[118:121]
	v_mfma_f32_16x16x32_bf16 v[114:117], v[142:145], v[196:199], v[114:117]
	v_mfma_f32_16x16x32_bf16 v[110:113], v[134:137], v[208:211], v[110:113]
	v_mfma_f32_16x16x32_bf16 v[106:109], v[142:145], v[208:211], v[106:109]
	v_mfma_f32_16x16x32_bf16 v[102:105], v[134:137], v[216:219], v[102:105]
	v_mfma_f32_16x16x32_bf16 v[98:101], v[142:145], v[216:219], v[98:101]
	v_mfma_f32_16x16x32_bf16 v[126:129], v[138:141], v[192:195], v[126:129]
	v_mfma_f32_16x16x32_bf16 v[122:125], v[146:149], v[192:195], v[122:125]
	v_mfma_f32_16x16x32_bf16 v[118:121], v[138:141], v[200:203], v[118:121]
	v_mfma_f32_16x16x32_bf16 v[114:117], v[146:149], v[200:203], v[114:117]
	v_mfma_f32_16x16x32_bf16 v[110:113], v[138:141], v[212:215], v[110:113]
	v_mfma_f32_16x16x32_bf16 v[106:109], v[146:149], v[212:215], v[106:109]
	v_mfma_f32_16x16x32_bf16 v[102:105], v[138:141], v[230:233], v[102:105]
	v_mfma_f32_16x16x32_bf16 v[98:101], v[146:149], v[230:233], v[98:101]
	v_mfma_f32_16x16x32_bf16 v[94:97], v[150:153], v[188:191], v[94:97]
	v_mfma_f32_16x16x32_bf16 v[90:93], v[162:165], v[188:191], v[90:93]
	v_mfma_f32_16x16x32_bf16 v[86:89], v[150:153], v[196:199], v[86:89]
	v_mfma_f32_16x16x32_bf16 v[82:85], v[162:165], v[196:199], v[82:85]
	v_mfma_f32_16x16x32_bf16 v[78:81], v[150:153], v[208:211], v[78:81]
	v_mfma_f32_16x16x32_bf16 v[74:77], v[162:165], v[208:211], v[74:77]
	v_mfma_f32_16x16x32_bf16 v[70:73], v[150:153], v[216:219], v[70:73]
	v_mfma_f32_16x16x32_bf16 v[66:69], v[162:165], v[216:219], v[66:69]
	v_mfma_f32_16x16x32_bf16 v[94:97], v[154:157], v[192:195], v[94:97]
	v_mfma_f32_16x16x32_bf16 v[90:93], v[184:187], v[192:195], v[90:93]
	v_mfma_f32_16x16x32_bf16 v[86:89], v[154:157], v[200:203], v[86:89]
	v_mfma_f32_16x16x32_bf16 v[82:85], v[184:187], v[200:203], v[82:85]
	v_mfma_f32_16x16x32_bf16 v[78:81], v[154:157], v[212:215], v[78:81]
	v_mfma_f32_16x16x32_bf16 v[74:77], v[184:187], v[212:215], v[74:77]
	v_mfma_f32_16x16x32_bf16 v[70:73], v[154:157], v[230:233], v[70:73]
	v_mfma_f32_16x16x32_bf16 v[66:69], v[184:187], v[230:233], v[66:69]
	s_barrier
; #define PG8_STAGE(bufoff, gbase, voff) do { _Pragma("unroll") for (int _i = 0; _i < 2; ++_i) \
;         __builtin_amdgcn_global_load_lds((const unsigned*)((const char*)(gbase) + (voff)[_i]), (LAS unsigned*)(lds + (bufoff) + ldsw + _i * 8192), 16, 0, 0); } while (0)
; #define PG8_LDA(dst, b, h) do { _Pragma("unroll") for (int m = 0; m < 4; ++m) _Pragma("unroll") for (int k = 0; k < 2; ++k) dst[m][k] = *(const LAS bf16x8*)(lds + PG8_SA(b, h) + aoff + m * 2048 + k * 1024); } while (0)
; #define PG8_MMA(ai, bj, At, Bt) do { __builtin_amdgcn_s_setprio(1); _Pragma("unroll") for (int m = 0; m < 4; ++m) _Pragma("unroll") for (int n = 0; n < 2; ++n) _Pragma("unroll") for (int k = 0; k < 2; ++k) \
;         acc[ai][bj][m][n] = __builtin_amdgcn_mfma_f32_16x16x32_bf16(Bt[n][k], At[m][k], acc[ai][bj][m][n], 0, 0, 0); __builtin_amdgcn_s_setprio(0); } while (0)
; #define PG8_WAIT_V(n) asm volatile("s_waitcnt vmcnt(" #n ")" ::: "memory")
; #define PG8_WAIT_L(n) asm volatile("s_waitcnt lgkmcnt(" #n ")" ::: "memory")
; #define PG8_BAR __builtin_amdgcn_s_barrier()
; #define PG8_SCHED __builtin_amdgcn_sched_barrier(0)
; template <class Epi, bool ALIGN_EPI = true>
; __device__ __forceinline__ void gemm_phase(LAS unsigned char* lds, const Gemm g, const Order& S, const Epi& E) {
;     ...
;             PG8_LDA(At, 1, 1); PG8_STAGE(PG8_SB(1, 0), b3, voffB); PG8_STAGE(PG8_SB(1, 1), b3 + hstepB, voffB); PG8_STAGE(PG8_SA(1, 0), a3, voffA);
;             PG8_WAIT_V(8); PG8_WAIT_L(0); PG8_BAR; PG8_MMA(1, 0, At, B0); PG8_MMA(1, 1, At, B1); PG8_BAR; PG8_SCHED;
;         }
;         if constexpr (ALIGN_EPI) { if (wr == 0) PG8_BAR; }
;         if (cur.S == 0) { if constexpr (Epi::PRELOAD) { if (ui < PRE_UNITS) E(acc, cur, wr, wc, fr, fq, pre + ui * 512); else E(acc, cur, wr, wc, fr, fq); } else E(acc, cur, wr, wc, fr, fq); }
	s_add_u32 s62, s60, 0x8000
	s_addc_u32 s63, s61, 0
	s_add_i32 s83, s83, s65
	v_lshl_add_u64 v[204:205], s[62:63], 0, v[206:207]
	s_mov_b32 m0, s83
	ds_read_b128 v[188:191], v183 offset:49152
	ds_read_b128 v[192:195], v183 offset:50176
	ds_read_b128 v[196:199], v183 offset:51200
	ds_read_b128 v[200:203], v183 offset:52224
	ds_read_b128 v[208:211], v183 offset:53248
	ds_read_b128 v[212:215], v183 offset:54272
	ds_read_b128 v[216:219], v183 offset:55296
	ds_read_b128 v[230:233], v183 offset:56320
	global_load_lds_dwordx4 v[204:205], off
	s_add_i32 m0, s83, 0x2000
	s_add_u32 s60, s60, 0xc000
	v_lshl_add_u64 v[204:205], s[62:63], 0, v[158:159]
	s_addc_u32 s61, s61, 0
	s_add_i32 s62, s84, s65
	global_load_lds_dwordx4 v[204:205], off
	v_lshl_add_u64 v[204:205], s[60:61], 0, v[206:207]
	s_mov_b32 m0, s62
	s_nop 0
	global_load_lds_dwordx4 v[204:205], off
	v_lshl_add_u64 v[204:205], s[60:61], 0, v[158:159]
	s_add_i32 m0, s62, 0x2000
	s_nop 0
	global_load_lds_dwordx4 v[204:205], off
	v_lshl_add_u64 v[204:205], s[58:59], 0, v[206:207]
	s_mov_b32 m0, s75
	s_nop 0
	global_load_lds_dwordx4 v[204:205], off
	v_lshl_add_u64 v[204:205], s[58:59], 0, v[158:159]
	s_mov_b32 m0, s76
	s_nop 0
	global_load_lds_dwordx4 v[204:205], off
	s_waitcnt vmcnt(8)
	s_waitcnt lgkmcnt(0)
	s_barrier
	s_waitcnt lgkmcnt(0)
	v_mfma_f32_16x16x32_bf16 v[62:65], v[134:137], v[188:191], v[62:65]
	v_mfma_f32_16x16x32_bf16 v[58:61], v[142:145], v[188:191], v[58:61]
	v_mfma_f32_16x16x32_bf16 v[54:57], v[134:137], v[196:199], v[54:57]
	v_mfma_f32_16x16x32_bf16 v[50:53], v[142:145], v[196:199], v[50:53]
	v_mfma_f32_16x16x32_bf16 v[46:49], v[134:137], v[208:211], v[46:49]
	v_mfma_f32_16x16x32_bf16 v[42:45], v[142:145], v[208:211], v[42:45]
	v_mfma_f32_16x16x32_bf16 v[38:41], v[134:137], v[216:219], v[38:41]
	v_mfma_f32_16x16x32_bf16 v[34:37], v[142:145], v[216:219], v[34:37]
	v_mfma_f32_16x16x32_bf16 v[62:65], v[138:141], v[192:195], v[62:65]
	v_mfma_f32_16x16x32_bf16 v[58:61], v[146:149], v[192:195], v[58:61]
	v_mfma_f32_16x16x32_bf16 v[54:57], v[138:141], v[200:203], v[54:57]
	v_mfma_f32_16x16x32_bf16 v[50:53], v[146:149], v[200:203], v[50:53]
	v_mfma_f32_16x16x32_bf16 v[46:49], v[138:141], v[212:215], v[46:49]
	v_mfma_f32_16x16x32_bf16 v[42:45], v[146:149], v[212:215], v[42:45]
	v_mfma_f32_16x16x32_bf16 v[38:41], v[138:141], v[230:233], v[38:41]
	v_mfma_f32_16x16x32_bf16 v[34:37], v[146:149], v[230:233], v[34:37]
	v_mfma_f32_16x16x32_bf16 v[30:33], v[150:153], v[188:191], v[30:33]
	v_mfma_f32_16x16x32_bf16 v[26:29], v[162:165], v[188:191], v[26:29]
	v_mfma_f32_16x16x32_bf16 v[22:25], v[150:153], v[196:199], v[22:25]
	v_mfma_f32_16x16x32_bf16 v[18:21], v[162:165], v[196:199], v[18:21]
	v_mfma_f32_16x16x32_bf16 v[14:17], v[150:153], v[208:211], v[14:17]
	v_mfma_f32_16x16x32_bf16 v[10:13], v[162:165], v[208:211], v[10:13]
	v_mfma_f32_16x16x32_bf16 v[6:9], v[150:153], v[216:219], v[6:9]
	v_mfma_f32_16x16x32_bf16 v[2:5], v[162:165], v[216:219], v[2:5]
	v_mfma_f32_16x16x32_bf16 v[30:33], v[154:157], v[192:195], v[30:33]
	v_mfma_f32_16x16x32_bf16 v[26:29], v[184:187], v[192:195], v[26:29]
	v_mfma_f32_16x16x32_bf16 v[22:25], v[154:157], v[200:203], v[22:25]
	v_mfma_f32_16x16x32_bf16 v[18:21], v[184:187], v[200:203], v[18:21]
	v_mfma_f32_16x16x32_bf16 v[14:17], v[154:157], v[212:215], v[14:17]
	v_mfma_f32_16x16x32_bf16 v[10:13], v[184:187], v[212:215], v[10:13]
	v_mfma_f32_16x16x32_bf16 v[6:9], v[154:157], v[230:233], v[6:9]
	v_mfma_f32_16x16x32_bf16 v[2:5], v[184:187], v[230:233], v[2:5]
	s_barrier
	s_add_i32 s82, s82, 2
	s_add_u32 s52, s52, 0x10000
	s_addc_u32 s53, s53, 0
	s_cmp_gt_u32 s82, 13
	s_cbranch_scc0 .LBB0_893
	s_and_b64 vcc, exec, s[42:43]
	s_cbranch_vccz .LBB0_899
	s_barrier
	s_mov_b64 s[52:53], -1
	s_cmp_gt_i32 s78, 5
	v_lshl_or_b32 v162, s4, 8, v182
	s_cbranch_scc1 .LBB0_900
